# two-level grid barrier (8 group counters in free ws words, atomic polls) replaces 22 of 25 cooperative-groups syncs; attention loop two tiles per barrier
# speedup vs baseline: 1.0343x; 1.0343x over previous
; __global__ void __launch_bounds__(NT) fwd_megakernel(Params p) {
;     ...
;   phase0a(p, lds);
;   grid.sync();
.LBB0_91:
	v_lshrrev_b32_e32 v1, 20, v0
	v_lshrrev_b32_e32 v0, 10, v0
	v_or_b32_e32 v0, v0, v1
	s_movk_i32 s0, 0x3ff
	v_and_or_b32 v0, v0, s0, v162
	s_waitcnt lgkmcnt(0)
	s_barrier
	v_cmp_eq_u32_e64 s[0:1], 0, v0
	s_mov_b64 s[10:11], exec
	s_nop 0
	v_writelane_b32 v254, s0, 34
	s_nop 1
	v_writelane_b32 v254, s1, 35
	s_and_b64 s[0:1], s[10:11], s[0:1]
	s_mov_b64 exec, s[0:1]
	s_cbranch_execz .LBB0_101
	v_readlane_b32 s6, v254, 4
	s_nop 3
	s_cmp_eq_u32 s6, 0
	s_cbranch_scc0 .Lgs_noinit
	v_readlane_b32 s6, v254, 2
	v_readlane_b32 s7, v254, 3
	s_nop 3
	s_load_dwordx2 s[8:9], s[6:7], 0x128
	v_mov_b32_e32 v0, 0
	v_mov_b32_e32 v1, 0
	s_waitcnt lgkmcnt(0)
	s_add_u32 s8, s8, 0x43a4000
	s_addc_u32 s9, s9, 0
	global_store_dword v0, v1, s[8:9] offset:64 sc0 sc1
	global_store_dword v0, v1, s[8:9] offset:128 sc0 sc1
	global_store_dword v0, v1, s[8:9] offset:512 sc0 sc1
	global_store_dword v0, v1, s[8:9] offset:768 sc0 sc1
	global_store_dword v0, v1, s[8:9] offset:544 sc0 sc1
	global_store_dword v0, v1, s[8:9] offset:800 sc0 sc1
	global_store_dword v0, v1, s[8:9] offset:576 sc0 sc1
	global_store_dword v0, v1, s[8:9] offset:832 sc0 sc1
	global_store_dword v0, v1, s[8:9] offset:608 sc0 sc1
	global_store_dword v0, v1, s[8:9] offset:864 sc0 sc1
	global_store_dword v0, v1, s[8:9] offset:640 sc0 sc1
	global_store_dword v0, v1, s[8:9] offset:896 sc0 sc1
	global_store_dword v0, v1, s[8:9] offset:672 sc0 sc1
	global_store_dword v0, v1, s[8:9] offset:928 sc0 sc1
	global_store_dword v0, v1, s[8:9] offset:704 sc0 sc1
	global_store_dword v0, v1, s[8:9] offset:960 sc0 sc1
	global_store_dword v0, v1, s[8:9] offset:736 sc0 sc1
	global_store_dword v0, v1, s[8:9] offset:992 sc0 sc1
.Lgs_noinit:
	s_mov_b32 s6, 0
	v_writelane_b32 v255, s6, 50
	v_readlane_b32 s0, v254, 0
	v_readlane_b32 s1, v254, 1
	buffer_wbl2 sc1
	s_waitcnt vmcnt(0)
	s_load_dwordx2 s[4:5], s[0:1], 0x58
	v_mov_b32_e32 v2, 0
	s_mov_b64 s[6:7], exec
	v_mbcnt_lo_u32_b32 v1, s6, 0
	v_mbcnt_hi_u32_b32 v1, s7, v1
	s_waitcnt lgkmcnt(0)
	global_load_dword v0, v2, s[4:5] offset:40
	v_cmp_eq_u32_e32 vcc, 0, v1
	s_and_saveexec_b64 s[8:9], vcc
	s_cbranch_execz .LBB0_94
	s_bcnt1_i32_b64 s0, s[6:7]
	v_mov_b32_e32 v3, s0
	global_atomic_add v3, v2, v3, s[4:5] offset:32 sc0

; __global__ void __launch_bounds__(NT) fwd_megakernel(Params p) {
;     ...
;   phase0a(p, lds);
;   grid.sync();
.LBB0_99:
	s_sleep 32
	global_load_dword v2, v0, s[4:5] offset:32 sc1
	s_waitcnt vmcnt(0)
	v_and_b32_e32 v2, 0xffff0000, v2
	v_cmp_ne_u32_e32 vcc, v2, v1
	s_or_b64 s[6:7], vcc, s[6:7]
	s_andn2_b64 exec, exec, s[6:7]
	s_cbranch_execnz .LBB0_99

; __global__ void __launch_bounds__(NT) fwd_megakernel(Params p) {
;     ...
;     phase_h1(p, hf);
;     grid.sync();
.LBB0_122:
	s_or_b64 exec, exec, s[4:5]
	v_readlane_b32 s0, v255, 3
	v_readlane_b32 s1, v255, 4
	s_xor_b64 s[0:1], s[0:1], -1
	v_writelane_b32 v255, s0, 14
	s_barrier
	s_nop 0
	v_writelane_b32 v255, s1, 15
	s_mov_b64 s[4:5], exec
	v_readlane_b32 s0, v254, 34
	v_readlane_b32 s1, v254, 35
	s_and_b64 s[0:1], s[4:5], s[0:1]
	s_mov_b64 exec, s[0:1]
	s_cbranch_execz .LBB0_132
	v_readlane_b32 s0, v254, 0
	v_readlane_b32 s1, v254, 1
	buffer_wbl2 sc1
	s_waitcnt vmcnt(0)
	v_readlane_b32 s0, v254, 2
	v_readlane_b32 s1, v254, 3
	v_readlane_b32 s24, v255, 50
	v_readlane_b32 s25, v254, 4
	v_readlane_b32 s80, v254, 5
	s_nop 3
	s_load_dwordx2 s[8:9], s[0:1], 0x128
	s_add_i32 s24, s24, 1
	v_writelane_b32 v255, s24, 50
	s_and_b32 s25, s25, 7
	s_sub_i32 s81, s80, s25
	s_add_i32 s81, s81, 7
	s_lshr_b32 s81, s81, 3
	s_mul_i32 s81, s81, s24
	s_min_u32 s80, s80, 8
	s_mul_i32 s80, s80, s24
	s_lshl_b32 s25, s25, 5
	v_mov_b32_e32 v0, s25
	v_mov_b32_e32 v1, 1
	s_waitcnt lgkmcnt(0)
	s_add_u32 s8, s8, 0x43a4000
	s_addc_u32 s9, s9, 0
	global_atomic_add v2, v0, v1, s[8:9] offset:512 sc0
	s_waitcnt vmcnt(0)
	v_readfirstlane_b32 s0, v2
	s_nop 3
	s_add_i32 s0, s0, 1
	s_cmp_eq_u32 s0, s81
	s_cbranch_scc0 .Lgs1_follower
	global_atomic_add v2, v153, v1, s[8:9] offset:64 sc0
	s_waitcnt vmcnt(0)
	v_readfirstlane_b32 s0, v2
	s_nop 3
	s_add_i32 s0, s0, 1
	s_cmp_eq_u32 s0, s80
	s_cbranch_scc0 .Lgs1_lwait
	global_atomic_add v153, v1, s[8:9] offset:128
	s_branch .Lgs1_lrel
.Lgs1_lwait:
	s_mov_b32 s1, 0
.Lgs1_lspin:
	s_sleep 2
	global_atomic_add v2, v153, v153, s[8:9] offset:128 sc0
	s_add_i32 s1, s1, 1
	s_waitcnt vmcnt(0)
	v_readfirstlane_b32 s0, v2
	s_nop 3
	s_cmp_ge_u32 s0, s24
	s_cbranch_scc1 .Lgs1_lrel
	s_cmp_lt_u32 s1, 0x4000
	s_cbranch_scc1 .Lgs1_lspin
.Lgs1_lrel:
	global_atomic_add v0, v1, s[8:9] offset:768
	s_branch .Lgs1_done

; __global__ void __launch_bounds__(NT) fwd_megakernel(Params p) {
;     ...
;     phase_h1(p, hf);
;     grid.sync();
.Lgs1_fspin:
	s_sleep 8
	global_atomic_add v2, v0, v153, s[8:9] offset:768 sc0
	s_add_i32 s1, s1, 1
	s_waitcnt vmcnt(0)
	v_readfirstlane_b32 s0, v2
	s_nop 3
	s_cmp_ge_u32 s0, s24
	s_cbranch_scc1 .Lgs1_done
	s_cmp_lt_u32 s1, 0x4000
	s_cbranch_scc1 .Lgs1_fspin
.Lgs1_done:
.LBB0_131:
	buffer_inv sc1

; __global__ void __launch_bounds__(NT) fwd_megakernel(Params p) {
;     ...
;     phase_gemm_in(p, hf, lds);
;     grid.sync();
.LBB0_159:
	s_waitcnt vmcnt(0)
	s_barrier
	s_mov_b64 s[4:5], exec
	v_readlane_b32 s0, v254, 34
	v_readlane_b32 s1, v254, 35
	s_and_b64 s[0:1], s[4:5], s[0:1]
	s_mov_b64 exec, s[0:1]
	s_cbranch_execz .LBB0_169
	v_readlane_b32 s0, v254, 0
	v_readlane_b32 s1, v254, 1
	buffer_wbl2 sc1
	s_waitcnt vmcnt(0)
	v_readlane_b32 s0, v254, 2
	v_readlane_b32 s1, v254, 3
	v_readlane_b32 s24, v255, 50
	v_readlane_b32 s25, v254, 4
	v_readlane_b32 s80, v254, 5
	s_nop 3
	s_load_dwordx2 s[8:9], s[0:1], 0x128
	s_add_i32 s24, s24, 1
	v_writelane_b32 v255, s24, 50
	s_and_b32 s25, s25, 7
	s_sub_i32 s81, s80, s25
	s_add_i32 s81, s81, 7
	s_lshr_b32 s81, s81, 3
	s_mul_i32 s81, s81, s24
	s_min_u32 s80, s80, 8
	s_mul_i32 s80, s80, s24
	s_lshl_b32 s25, s25, 5
	v_mov_b32_e32 v0, s25
	v_mov_b32_e32 v1, 1
	s_waitcnt lgkmcnt(0)
	s_add_u32 s8, s8, 0x43a4000
	s_addc_u32 s9, s9, 0
	global_atomic_add v2, v0, v1, s[8:9] offset:512 sc0
	s_waitcnt vmcnt(0)
	v_readfirstlane_b32 s0, v2
	s_nop 3
	s_add_i32 s0, s0, 1
	s_cmp_eq_u32 s0, s81
	s_cbranch_scc0 .Lgs2_follower
	global_atomic_add v2, v153, v1, s[8:9] offset:64 sc0
	s_waitcnt vmcnt(0)
	v_readfirstlane_b32 s0, v2
	s_nop 3
	s_add_i32 s0, s0, 1
	s_cmp_eq_u32 s0, s80
	s_cbranch_scc0 .Lgs2_lwait
	global_atomic_add v153, v1, s[8:9] offset:128
	s_branch .Lgs2_lrel

; DI int tidx() { int t = threadIdx.x; asm volatile("" : "+v"(t)); return t; }
; DI void attn_item(const Params& p, int L, int b, int h, int qb, float lam, char* lds) {
;   const int tid = tidx(), lane = tid & 63, wave = __builtin_amdgcn_readfirstlane(tid >> 6);
;   const int lq = lane & 31, hi = lane >> 5, rg = wave & 3, m = wave >> 2;
;   bf16_t* qg = (bf16_t*)(p.ws + OFF_Q);
;   const unsigned char* kg8 = (const unsigned char*)(p.ws + OFF_K) + ((size_t)b * L) * 1024 + h * 128;
;   const unsigned char* qg8 = (const unsigned char*)(p.ws + OFF_K) + OFF_Q8;
;   const bf16_t* vg = (const bf16_t*)(p.ws + OFF_V) + (size_t)b * L * 1024 + h * 128;
;   const size_t tok0 = (size_t)b * L + (size_t)qb * 128;
;   v8i_t qf8;
;   {
;     const uint4* qp = (const uint4*)(qg8 + (tok0 + rg * 32 + lq) * 1024 + h * 128 + m * 64 + hi * 32);
;     const uint4 q0 = qp[0], q1 = qp[1];
;     qf8[0] = q0.x; qf8[1] = q0.y; qf8[2] = q0.z; qf8[3] = q0.w; qf8[4] = q1.x; qf8[5] = q1.y; qf8[6] = q1.z; qf8[7] = q1.w;
;   }
;   float q2 = 0.f;
; #pragma unroll
;   for (int w = 0; w < 8; ++w) {
;     const float v0 = __builtin_amdgcn_cvt_f32_fp8(qf8[w], 0), v1 = __builtin_amdgcn_cvt_f32_fp8(qf8[w], 1);
;     const float v2 = __builtin_amdgcn_cvt_f32_fp8(qf8[w], 2), v3 = __builtin_amdgcn_cvt_f32_fp8(qf8[w], 3);
;     q2 += v0 * v0 + v1 * v1 + v2 * v2 + v3 * v3;
;   }
;   q2 = xhalf_sum(q2);
;   const float kmx2 = ((const float*)(p.ws + OFF_KMAX))[(b * 8 + h) * 2 + m];
;   const float sinit = -(sqrtf(q2 * kmx2) * 1.09f + 0.125f);
;   f32x16 oacc[4];
; #pragma unroll
;   for (int e = 0; e < 4; ++e)
; #pragma unroll
;     for (int i = 0; i < 16; ++i) oacc[e][i] = 0.f;
;   float lsum = 0.f;
.LBB0_202:
	s_and_b32 s0, s21, 7
	s_lshl_b32 s22, s0, 8
	s_ashr_i32 s0, s83, 8
	s_abs_i32 s5, s0
	s_mul_hi_u32 s8, s5, s82
	s_mul_i32 s9, s8, s56
	s_sub_i32 s5, s5, s9
	s_and_b32 s59, s83, 7
	s_bfe_u32 s1, s83, 0x50003
	s_ashr_i32 s4, s83, 31
	s_add_i32 s9, s8, 1
	s_sub_i32 s23, s5, s56
	s_cmp_ge_u32 s5, s56
	s_cselect_b32 s8, s9, s8
	s_cselect_b32 s5, s23, s5
	s_add_i32 s9, s8, 1
	s_cmp_ge_u32 s5, s56
	s_cselect_b32 s5, s9, s8
	s_xor_b32 s5, s5, s4
	s_sub_i32 s4, s5, s4
	s_mul_i32 s5, s4, s56
	s_sub_i32 s0, s0, s5
	s_lshl_b32 s0, s0, 5
	v_mov_b32_e32 v8, v162
	s_or_b32 s84, s0, s1
	s_ashr_i32 s5, s4, 31
	v_readfirstlane_b32 s0, v8
	s_ashr_i32 s68, s0, 6
	s_lshl_b64 vcc, s[4:5], s57
	s_and_b32 s1, s68, 3
	s_ashr_i32 s58, s0, 8
	s_lshl_b64 s[24:25], vcc, 10
	s_lshl_b32 s96, s59, 7
	s_lshl_b64 s[8:9], vcc, 11
	s_add_u32 s69, s74, s8
	s_addc_u32 s80, s75, s9
	s_ashr_i32 s85, s84, 31
	s_lshl_b64 s[84:85], s[84:85], 7
	v_and_b32_e32 v9, 31, v8
	s_add_u32 s5, s84, vcc_lo
	s_addc_u32 s23, s85, vcc_hi
	v_or_b32_e32 v0, s5, v9
	v_lshl_or_b32 v0, s1, 5, v0
	v_mov_b32_e32 v1, s23
	v_readlane_b32 s12, v254, 12
	v_lshlrev_b64 v[154:155], 10, v[0:1]
	v_readlane_b32 s13, v254, 13
	s_lshl_b32 s84, s58, 6
	s_ashr_i32 s85, s84, 31
	v_lshl_add_u64 v[0:1], s[12:13], 0, v[154:155]
	v_lshl_add_u64 v[0:1], v[0:1], 0, s[96:97]
	v_lshl_add_u64 v[0:1], v[0:1], 0, s[84:85]
	v_and_b32_e32 v152, 32, v8
	v_lshl_add_u64 v[0:1], v[0:1], 0, v[152:153]
	global_load_dwordx4 v[144:147], v[0:1], off
	global_load_dwordx4 v[148:151], v[0:1], off offset:16
	s_add_u32 s5, s30, s24
	s_addc_u32 s23, s31, s25
	s_add_u32 s24, s5, s96
	s_addc_u32 s25, s23, 0
	s_lshl_b32 s4, s4, 4
	s_lshl_b32 s5, s59, 1
	s_or_b32 s4, s4, s5
	s_add_i32 s4, s4, s58
	s_ashr_i32 s5, s4, 31
	s_lshl_b64 s[4:5], s[4:5], 2
	v_readlane_b32 s12, v254, 20
	v_readlane_b32 s13, v254, 21
	s_add_u32 s4, s12, s4
	s_addc_u32 s5, s13, s5
	global_load_dword v10, v153, s[4:5]
	s_mov_b32 s4, 0xf800000
	s_mov_b64 s[12:13], 0x10000
	s_barrier
	v_bfe_u32 v152, v8, 5, 1
	v_and_b32_e32 v182, 63, v8
	v_mov_b32_e32 v188, 0
	s_mov_b32 s23, 5
	s_mov_b32 s84, 0x18000
	v_mov_b32_e32 v48, 0
	v_mov_b32_e32 v49, v188
	v_mov_b32_e32 v50, v188
	v_mov_b32_e32 v51, v188
	v_mov_b32_e32 v52, v188
	v_mov_b32_e32 v53, v188
	v_mov_b32_e32 v54, v188
	v_mov_b32_e32 v55, v188
	v_mov_b32_e32 v56, v188
	v_mov_b32_e32 v57, v188
	v_mov_b32_e32 v58, v188
	v_mov_b32_e32 v59, v188
	v_mov_b32_e32 v60, v188
	v_mov_b32_e32 v61, v188
	v_mov_b32_e32 v62, v188
	v_mov_b32_e32 v63, v188
	v_mov_b32_e32 v32, 0
	v_mov_b32_e32 v33, v188
	v_mov_b32_e32 v34, v188
	v_mov_b32_e32 v35, v188
	v_mov_b32_e32 v36, v188
	v_mov_b32_e32 v37, v188
	v_mov_b32_e32 v38, v188
	v_mov_b32_e32 v39, v188
	v_mov_b32_e32 v40, v188
	v_mov_b32_e32 v41, v188
	v_mov_b32_e32 v42, v188
	v_mov_b32_e32 v43, v188
	v_mov_b32_e32 v44, v188
	v_mov_b32_e32 v45, v188
	v_mov_b32_e32 v46, v188
	v_mov_b32_e32 v47, v188
	v_mov_b32_e32 v27, v188
	v_mov_b32_e32 v28, v188
	v_mov_b32_e32 v29, v188
	v_mov_b32_e32 v30, v188
	v_mov_b32_e32 v31, v188
	s_waitcnt vmcnt(2)
	v_cvt_f32_fp8_sdwa v1, v144 src0_sel:BYTE_1
	v_cvt_f32_fp8_sdwa v5, v145 src0_sel:BYTE_1
	v_cvt_f32_fp8_e32 v0, v144
	v_cvt_f32_fp8_e32 v4, v145
	v_cvt_f32_fp8_sdwa v12, v146 src0_sel:BYTE_1
	v_cvt_f32_fp8_sdwa v2, v144 src0_sel:BYTE_2
	v_cvt_f32_fp8_sdwa v6, v145 src0_sel:BYTE_2
	v_cvt_f32_fp8_e32 v11, v146
	v_cvt_f32_fp8_sdwa v16, v147 src0_sel:BYTE_1
	v_cvt_f32_fp8_sdwa v3, v144 src0_sel:BYTE_3
	v_cvt_f32_fp8_sdwa v7, v145 src0_sel:BYTE_3
	v_cvt_f32_fp8_sdwa v13, v146 src0_sel:BYTE_2
	v_cvt_f32_fp8_e32 v15, v147
	s_waitcnt vmcnt(1)
	v_cvt_f32_fp8_sdwa v20, v148 src0_sel:BYTE_1
	v_cvt_f32_fp8_sdwa v14, v146 src0_sel:BYTE_3
	v_cvt_f32_fp8_sdwa v17, v147 src0_sel:BYTE_2
	v_cvt_f32_fp8_e32 v19, v148
	v_cvt_f32_fp8_sdwa v24, v149 src0_sel:BYTE_1
	v_mul_f32_e32 v1, v1, v1
	v_mul_f32_e32 v5, v5, v5
	v_cvt_f32_fp8_sdwa v18, v147 src0_sel:BYTE_3
	v_cvt_f32_fp8_sdwa v21, v148 src0_sel:BYTE_2
	v_cvt_f32_fp8_e32 v23, v149
	v_mul_f32_e32 v12, v12, v12
	v_fmac_f32_e32 v1, v0, v0
	v_fmac_f32_e32 v5, v4, v4
	v_cvt_f32_fp8_sdwa v22, v148 src0_sel:BYTE_3
	v_cvt_f32_fp8_sdwa v25, v149 src0_sel:BYTE_2
	v_mul_f32_e32 v16, v16, v16
	v_fmac_f32_e32 v12, v11, v11
	v_fmac_f32_e32 v1, v2, v2
	v_fmac_f32_e32 v5, v6, v6
	v_cvt_f32_fp8_sdwa v26, v149 src0_sel:BYTE_3
	v_mul_f32_e32 v20, v20, v20
	v_fmac_f32_e32 v16, v15, v15
	v_fmac_f32_e32 v12, v13, v13
	v_fmac_f32_e32 v1, v3, v3
	v_fmac_f32_e32 v5, v7, v7
	v_mul_f32_e32 v24, v24, v24
	v_fmac_f32_e32 v20, v19, v19
	v_fmac_f32_e32 v16, v17, v17
	v_fmac_f32_e32 v12, v14, v14
	v_add_f32_e32 v0, v1, v5
	v_fmac_f32_e32 v24, v23, v23
	v_fmac_f32_e32 v20, v21, v21
	v_fmac_f32_e32 v16, v18, v18
	v_add_f32_e32 v0, v0, v12
	v_fmac_f32_e32 v24, v25, v25
	v_fmac_f32_e32 v20, v22, v22
	v_add_f32_e32 v0, v0, v16
	v_fmac_f32_e32 v24, v26, v26
	v_add_f32_e32 v0, v0, v20
	v_cvt_f32_fp8_sdwa v2, v150 src0_sel:BYTE_1
	v_cvt_f32_fp8_sdwa v3, v151 src0_sel:BYTE_1
	v_add_f32_e32 v11, v0, v24
	v_cvt_f32_fp8_e32 v0, v150
	v_cvt_f32_fp8_e32 v1, v151
	v_cvt_f32_fp8_sdwa v4, v150 src0_sel:BYTE_2
	v_cvt_f32_fp8_sdwa v5, v151 src0_sel:BYTE_2
	v_cvt_f32_fp8_sdwa v6, v150 src0_sel:BYTE_3
	v_cvt_f32_fp8_sdwa v7, v151 src0_sel:BYTE_3
	v_pk_mul_f32 v[2:3], v[2:3], v[2:3]
	v_bfe_u32 v13, v8, 2, 2
	v_pk_fma_f32 v[0:1], v[0:1], v[0:1], v[2:3]
	v_bfe_u32 v16, v8, 1, 1
	v_pk_fma_f32 v[0:1], v[4:5], v[4:5], v[0:1]
	v_lshlrev_b32_e32 v14, 10, v152
	v_pk_fma_f32 v[0:1], v[6:7], v[6:7], v[0:1]
	v_lshlrev_b32_e32 v15, 8, v13
	v_add_f32_e32 v0, v11, v0
	v_add_f32_e32 v0, v0, v1
	v_mov_b32_e32 v1, v0
	s_nop 1
	v_permlane32_swap_b32_e32 v0, v1
	v_add_f32_e32 v0, v0, v1
	s_waitcnt vmcnt(0)
; #define LDS3 __attribute__((address_space(3)))
; #define RAW_BARRIER() do { asm volatile("s_waitcnt lgkmcnt(0)" ::: "memory"); __builtin_amdgcn_s_barrier(); } while (0)
; DI void attn_item(const Params& p, int L, int b, int h, int qb, float lam, char* lds) {
;     ...
;   const float sinit = -(sqrtf(q2 * kmx2) * 1.09f + 0.125f);
;   f32x16 oacc[4];
; #pragma unroll
;   for (int e = 0; e < 4; ++e)
; #pragma unroll
;     for (int i = 0; i < 16; ++i) oacc[e][i] = 0.f;
;   float lsum = 0.f;
;   const int nkt = L / 64;
;   const int krow = wave * 8 + (lane >> 3);
;   const int gk = krow * 1024 + (((lane & 7) ^ ((krow >> 1) & 7)) * 16);
;   const int drow = wave * 8 + (lane >> 4), dcp = lane & 15;
;   const int gv0 = drow * 1024 + ((dcp ^ ((drow & 3) << 2)) * 8), gv1 = (drow + 4) * 1024 + ((dcp ^ (((drow + 4) & 3) << 2)) * 8);
;   auto dma_tile = [&](int j) {
;     char* st = lds + (j & 3) * A_STAGE;
;     const unsigned char* kt = kg8 + (size_t)min(j + 1, nkt - 1) * 64 * 1024;
;     const bf16_t* vt = vg + (size_t)j * 64 * 1024;
;     __builtin_amdgcn_global_load_lds((const unsigned*)(kt + gk), (LDS3 unsigned*)(st + wave * 1024), 16, 0, 0);
;     __builtin_amdgcn_global_load_lds((const unsigned*)(vt + gv0), (LDS3 unsigned*)(st + A_KB + wave * 8 * 256), 16, 0, 0);
;     __builtin_amdgcn_global_load_lds((const unsigned*)(vt + gv1), (LDS3 unsigned*)(st + A_KB + wave * 8 * 256 + 4 * 256), 16, 0, 0);
;   };
;   __syncthreads();
;   __builtin_amdgcn_global_load_lds((const unsigned*)(kg8 + gk), (LDS3 unsigned*)(lds + 3 * A_STAGE + wave * 1024), 16, 0, 0);
;   dma_tile(0); dma_tile(1); dma_tile(2);
;   LDS3 char* const l3 = (LDS3 char*)lds;
;   int vro[4];
;   const int kro = lq * 128 + (((m * 4 + hi * 2) ^ ((lq >> 1) & 7)) * 16);
;   {
;     const int tq = (lane & 15) >> 2, tp = lane & 3, blk = (lane >> 4) & 1;
; #pragma unroll
;     for (int eb = 0; eb < 4; ++eb) vro[eb] = A_KB + (4 * hi + tq) * 256 + ((((eb ^ tq) * 4) + blk * 2 + (tp >> 1)) * 16) + (tp & 1) * 8;
;   }
;     ...
;   const unsigned lds_addr0 = (unsigned)(size_t)lds;
;     ...
;   f32x16 sA0, sA1, sB0, sB1;
;   f32x16 sv;
; #pragma unroll
;   for (int i = 0; i < 16; ++i) sv[i] = sinit;
;     ...
;   asm volatile("s_waitcnt vmcnt(0)" ::: "memory");
;   RAW_BARRIER();
;   {
;     v8i_t k0, k1;
;     LDK8(k0, 3 * A_STAGE + kro) LDK8(k1, 3 * A_STAGE + kro + 32 * 128)
;     sA0 = QK8(k0, sv); sA1 = QK8(k1, sv);
;   }
	v_mul_f32_e32 v0, v10, v0
	v_mul_f32_e32 v1, 0x4f800000, v0
	v_cmp_gt_f32_e32 vcc, s4, v0
	v_bfe_u32 v10, v8, 3, 3
	v_bfe_u32 v11, v8, 4, 2
	v_cndmask_b32_e32 v0, v0, v1, vcc
	v_sqrt_f32_e32 v1, v0
	v_mov_b32_e32 v17, v188
	v_mov_b32_e32 v18, v188
	v_mov_b32_e32 v19, v188
	v_add_u32_e32 v2, -1, v1
	v_fma_f32 v3, -v2, v1, v0
	v_cmp_ge_f32_e64 s[4:5], 0, v3
	v_add_u32_e32 v3, 1, v1
	v_mov_b32_e32 v20, v188
	v_cndmask_b32_e64 v2, v1, v2, s[4:5]
	v_fma_f32 v1, -v3, v1, v0
	v_cmp_lt_f32_e64 s[4:5], 0, v1
	v_mov_b32_e32 v21, v188
	v_mov_b32_e32 v22, v188
	v_cndmask_b32_e64 v1, v2, v3, s[4:5]
	v_mul_f32_e32 v2, 0x37800000, v1
	s_lshl_b32 s4, s59, 8
	v_cndmask_b32_e32 v1, v1, v2, vcc
	v_cmp_class_f32_e32 vcc, v0, v164
	s_add_u32 s4, s69, s4
	s_addc_u32 s5, s80, 0
	v_cndmask_b32_e32 v0, v1, v0, vcc
	s_lshl_b32 s59, s68, 3
	v_fmamk_f32 v6, v0, 0x3f8b851f, v165
	v_or_b32_e32 v0, s59, v10
	v_lshlrev_b32_e32 v1, 10, v0
	v_lshrrev_b32_e32 v0, 1, v0
	v_xor_b32_e32 v0, v0, v8
	v_lshlrev_b32_e32 v0, 4, v0
	s_movk_i32 s69, 0x70
	v_and_or_b32 v0, v0, s69, v1
	v_or_b32_e32 v1, s59, v11
	v_and_b32_e32 v2, 15, v8
	v_lshlrev_b32_e32 v1, 10, v1
	v_lshlrev_b32_e32 v3, 5, v11
	v_lshlrev_b32_e32 v2, 3, v2
	v_xor_b32_e32 v12, v3, v2
	v_bitop3_b32 v2, v1, v3, v2 bitop3:0xf6
	v_ashrrev_i32_e32 v1, 31, v0
	s_lshl_b32 s59, s68, 10
	v_lshl_add_u64 v[156:157], s[24:25], 0, v[0:1]
	s_add_i32 m0, s59, 0x18000
	v_lshl_add_u64 v[0:1], v[156:157], 0, s[12:13]
	global_load_lds_dwordx4 v[156:157], off
	s_mov_b32 m0, s59
	v_ashrrev_i32_e32 v3, 31, v2
	v_or_b32_e32 v4, 0x1000, v2
	global_load_lds_dwordx4 v[0:1], off
	v_lshlrev_b64 v[0:1], 1, v[2:3]
	s_add_i32 s69, s59, s59
	v_lshl_add_u64 v[2:3], s[4:5], 0, v[0:1]
	s_add_i32 m0, s69, 0x4000
	v_ashrrev_i32_e32 v5, 31, v4
	s_lshl_b32 s85, s68, 11
	global_load_lds_dwordx4 v[2:3], off
	v_lshlrev_b64 v[2:3], 1, v[4:5]
	s_add_i32 m0, s69, 0x4400
	v_lshl_add_u64 v[4:5], s[4:5], 0, v[2:3]
	s_add_u32 s24, s4, 0x20000
	global_load_lds_dwordx4 v[4:5], off
	s_addc_u32 s25, s5, 0
	v_lshl_add_u64 v[4:5], v[156:157], 0, s[44:45]
	s_add_i32 m0, s59, 0x8000
	s_mov_b64 s[12:13], 0x30000
	global_load_lds_dwordx4 v[4:5], off
	v_lshl_add_u64 v[4:5], s[24:25], 0, v[0:1]
	s_add_i32 m0, s69, 0xc000
	v_xor_b32_e32 v64, 0x80000000, v6
	global_load_lds_dwordx4 v[4:5], off
	s_add_i32 m0, s69, 0xc400
	v_lshl_add_u64 v[4:5], s[24:25], 0, v[2:3]
	s_add_u32 s4, s4, 0x40000
	global_load_lds_dwordx4 v[4:5], off
	s_addc_u32 s5, s5, 0
	v_lshl_add_u64 v[4:5], v[156:157], 0, s[12:13]
	s_add_i32 m0, s59, 0x10000
	v_lshl_add_u64 v[0:1], s[4:5], 0, v[0:1]
	global_load_lds_dwordx4 v[4:5], off
	s_add_i32 m0, s85, 0x14000
	v_mov_b32_e32 v65, v64
	global_load_lds_dwordx4 v[0:1], off
	v_lshl_add_u64 v[0:1], s[4:5], 0, v[2:3]
	s_add_i32 m0, s85, 0x14400
	s_lshl_b32 s4, s58, 2
	global_load_lds_dwordx4 v[0:1], off
	v_lshlrev_b32_e32 v0, 1, v152
	v_bfe_u32 v1, v8, 1, 3
	v_bitop3_b32 v0, s4, v1, v0 bitop3:0x36
	v_lshlrev_b32_e32 v1, 7, v9
	v_lshl_add_u32 v183, v0, 4, v1
	v_add_u32_e32 v0, 0x18000, v183
	s_waitcnt vmcnt(0)
	v_xor_b32_e32 v4, 16, v0
	s_waitcnt lgkmcnt(0)
	s_barrier
	ds_read_b128 v[0:3], v0
	ds_read_b128 v[4:7], v4
	v_mov_b32_e32 v66, v64
	v_mov_b32_e32 v67, v64
	v_mov_b32_e32 v68, v64
	v_mov_b32_e32 v69, v64
	v_mov_b32_e32 v70, v64
	v_mov_b32_e32 v71, v64
	v_mov_b32_e32 v72, v64
	v_mov_b32_e32 v73, v64
	v_mov_b32_e32 v74, v64
	v_mov_b32_e32 v75, v64
	v_mov_b32_e32 v76, v64
	v_mov_b32_e32 v77, v64
	v_mov_b32_e32 v78, v64
	v_mov_b32_e32 v79, v64
	v_and_or_b32 v9, v10, 2, v16
	v_lshlrev_b32_e32 v10, 6, v13
	s_waitcnt lgkmcnt(0)
	v_mfma_scale_f32_32x32x64_f8f6f4 v[96:111], v[0:7], v[144:151], v[64:79], v166, v166 op_sel_hi:[0,0,0]
	v_lshlrev_b32_e32 v0, 3, v8
	v_and_b32_e32 v8, 8, v0
	v_add_u32_e32 v0, 0x19000, v183
	v_xor_b32_e32 v4, 16, v0
	ds_read_b128 v[0:3], v0
	ds_read_b128 v[4:7], v4
	v_or3_b32 v8, v15, v8, v14
	v_lshl_or_b32 v9, v9, 4, v10
	s_movk_i32 s4, 0x4040
	v_bitop3_b32 v185, v9, s4, v8 bitop3:0x36
	s_movk_i32 s4, 0x4080
	v_bitop3_b32 v186, v9, s4, v8 bitop3:0x36
	s_movk_i32 s4, 0x40c0
	v_bitop3_b32 v187, v9, s4, v8 bitop3:0x36
	s_lshl_b32 s4, s68, 13
	v_or_b32_e32 v10, v9, v8
	s_waitcnt lgkmcnt(0)
	v_mfma_scale_f32_32x32x64_f8f6f4 v[80:95], v[0:7], v[144:151], v[64:79], v166, v166 op_sel_hi:[0,0,0]
	v_lshlrev_b32_e32 v0, 10, v11
	v_or3_b32 v0, v12, s4, v0
	v_ashrrev_i32_e32 v1, 31, v0
	v_lshlrev_b64 v[158:159], 1, v[0:1]
	s_or_b32 s4, s8, s22
	v_or_b32_e32 v0, 0x1000, v0
	s_add_u32 s4, s10, s4
	v_ashrrev_i32_e32 v1, 31, v0
	v_or_b32_e32 v184, 0x4000, v10
	s_addc_u32 s5, s11, s9
	v_lshlrev_b64 v[160:161], 1, v[0:1]
	v_mov_b32_e32 v16, 0
	v_mov_b32_e32 v23, v188
	v_mov_b32_e32 v24, v188
	v_mov_b32_e32 v25, v188
	v_mov_b32_e32 v26, v188
	v_mov_b32_e32 v0, 0
	v_mov_b32_e32 v1, v188
	v_mov_b32_e32 v2, v188
	v_mov_b32_e32 v3, v188
	v_mov_b32_e32 v4, v188
	v_mov_b32_e32 v5, v188
	v_mov_b32_e32 v6, v188
	v_mov_b32_e32 v7, v188
	v_mov_b32_e32 v8, v188
	v_mov_b32_e32 v9, v188
	v_mov_b32_e32 v10, v188
	v_mov_b32_e32 v11, v188
	v_mov_b32_e32 v12, v188
	v_mov_b32_e32 v13, v188
	v_mov_b32_e32 v14, v188
	v_mov_b32_e32 v15, v188
	v_mov_b32_e32 v238, 0
	v_mov_b32_e32 v239, 0
	v_mov_b32_e32 v240, 0
	v_mov_b32_e32 v241, 0
	v_mov_b32_e32 v242, 0
	v_mov_b32_e32 v243, 0
	v_mov_b32_e32 v244, 0
	v_mov_b32_e32 v245, 0
	v_mov_b32_e32 v246, 0
	v_mov_b32_e32 v247, 0
	v_mov_b32_e32 v248, 0
	v_mov_b32_e32 v249, 0
	v_mov_b32_e32 v250, 0
	v_mov_b32_e32 v251, 0
	v_mov_b32_e32 v252, 0
	v_mov_b32_e32 v253, 0
	v_mov_b32_e32 v132, 0
	v_mov_b32_e32 v133, 0
	v_mov_b32_e32 v134, 0
	v_mov_b32_e32 v135, 0
	v_mov_b32_e32 v189, 0
	s_mov_b32 s23, 0
	s_mov_b32 s84, 0
	s_mov_b32 s25, 0
	s_mov_b32 s9, 0
	s_mov_b32 s68, 0x10000
	s_add_i32 s69, s68, s85
	s_add_i32 s22, s68, s59
	s_add_u32 s80, s4, s86
	s_addc_u32 s81, s5, s87
	s_mov_b32 s4, s80
	s_mov_b32 s5, s81
	s_sub_u32 s80, s80, 0x20000
	s_subb_u32 s81, s81, 0
	s_mov_b32 s24, 0x30000
	s_lshl_b32 s12, s77, 16
	s_mov_b32 s8, 0x40000
	s_min_u32 s8, s8, s12
	s_add_i32 s13, s76, -2
	s_cmp_eq_u32 s58, 1
	s_cbranch_scc0 .Lat_noprio
	s_setprio 1
; #define RAW_BARRIER() do { asm volatile("s_waitcnt lgkmcnt(0)" ::: "memory"); __builtin_amdgcn_s_barrier(); } while (0)
; #define SB() __builtin_amdgcn_sched_barrier(0)
; #define MV(g, st)                                                                                                     \
;   _Pragma("unroll") for (int eb = 0; eb < 4; ++eb)                                                                    \
;     oacc[eb] = MFMA32(__builtin_shufflevector(vlo[g][eb], vhi[g][eb], 0, 1, 2, 3, 4, 5, 6, 7), pf[st], oacc[eb]);
; #define EXP4(cx, i0) _Pragma("unroll") for (int i = (i0); i < (i0) + 4; ++i) { cx[i] = __builtin_amdgcn_exp2f(cx[i]); ps += cx[i]; }
; #define QK8(kf, cinit) __builtin_amdgcn_mfma_scale_f32_32x32x64_f8f6f4(kf, qf8, cinit, 0, 0, 0, 0x7F7F7F7F, 0, 0x7F7F7F7F)
; DI void attn_item(const Params& p, int L, int b, int h, int qb, float lam, char* lds) {
;     ...
;   auto step = [&](int t, f32x16& c0, f32x16& c1, f32x16& n0, f32x16& n1) {
;     if (t + 2 < nkt) asm volatile("s_waitcnt vmcnt(6)" ::: "memory");
;     else if (t + 1 < nkt) asm volatile("s_waitcnt vmcnt(3)" ::: "memory");
;     else asm volatile("s_waitcnt vmcnt(0)" ::: "memory");
;     RAW_BARRIER();
;     const int so = (t & 3) * A_STAGE;
;     int kad = so + kro, vad[4];
;     asm volatile("" : "+v"(kad));
; #pragma unroll
;     for (int i = 0; i < 4; ++i) { vad[i] = (int)lds_addr0 + so + vro[i]; asm volatile("" : "+v"(vad[i])); }
;     if (t + 3 < nkt) dma_tile(t + 3);
;     bf16x8 pf[4];
;     v8i_t kf0, kf1;
;     s16x4 vlo[2][4], vhi[2][4];
;     float ps = 0.f;
;     SB();
;     LDK8(kf0, kad) LDK8(kf1, kad + 32 * 128) RV(0, 0)
;     SB();
;     n0 = QK8(kf0, sv); EXP4(c0, 0) SB();
;     EXP4(c0, 4) PACK(pf[0], c0, 0) SB();
;     n1 = QK8(kf1, sv); EXP4(c0, 8) SB();
;     RV(1, 1) SB(); EXP4(c0, 12) PACK(pf[1], c0, 8) SB();
;     WAITV(8, 0) SB(); MVH(0, 0, 0) EXP4(c1, 0) SB(); MVH(0, 0, 2) EXP4(c1, 4) PACK(pf[2], c1, 0) SB();
;     RV(0, 2) SB(); WAITV(8, 1) SB(); MVH(1, 1, 0) EXP4(c1, 8) SB(); MVH(1, 1, 2) EXP4(c1, 12) PACK(pf[3], c1, 8) SB();
;     RV(1, 3) SB(); WAITV(8, 0) SB(); MV(0, 2) SB();
;     WAITV(0, 1) SB(); MV(1, 3) SB();
;     lsum += ps;
;   };
.Lat_noprio:
.Lat_top:
	s_waitcnt vmcnt(0)
	s_waitcnt lgkmcnt(0)
	s_barrier
	v_mfma_f32_32x32x16_bf16 v[48:63], v[238:241], v[132:135], v[48:63]
	v_add_u32_e32 v170, s84, v184
	v_add_u32_e32 v171, s84, v185
	ds_read_b64_tr_b16 v[190:191], v170 offset:0
	ds_read_b64_tr_b16 v[192:193], v170 offset:2048
	v_add_u32_e32 v172, s84, v186
	ds_read_b64_tr_b16 v[194:195], v171 offset:0
	ds_read_b64_tr_b16 v[196:197], v171 offset:2048
	v_mfma_f32_32x32x16_bf16 v[32:47], v[242:245], v[132:135], v[32:47]
	v_add_u32_e32 v173, s84, v187
	ds_read_b64_tr_b16 v[198:199], v172 offset:0
	ds_read_b64_tr_b16 v[200:201], v172 offset:2048
	ds_read_b64_tr_b16 v[202:203], v173 offset:0
	ds_read_b64_tr_b16 v[204:205], v173 offset:2048
	v_add_u32_e32 v136, s84, v183
	v_xor_b32_e32 v137, 16, v136
	v_exp_f32_e32 v96, v96
	v_exp_f32_e32 v97, v97
	v_add_f32_e32 v188, v96, v188
	v_cvt_pk_bf16_f32 v128, v96, v97
	v_add_f32_e32 v189, v97, v189
	v_mfma_f32_32x32x16_bf16 v[16:31], v[246:249], v[132:135], v[16:31]
	v_exp_f32_e32 v98, v98
	v_exp_f32_e32 v99, v99
	v_add_f32_e32 v188, v98, v188
	v_cvt_pk_bf16_f32 v129, v98, v99
	v_add_f32_e32 v189, v99, v189
	v_mfma_f32_32x32x16_bf16 v[0:15], v[250:253], v[132:135], v[0:15]
	v_exp_f32_e32 v100, v100
	v_exp_f32_e32 v101, v101
	v_add_f32_e32 v188, v100, v188
	v_cvt_pk_bf16_f32 v130, v100, v101
	v_add_f32_e32 v189, v101, v189
	v_exp_f32_e32 v102, v102
	v_exp_f32_e32 v103, v103
	v_add_f32_e32 v188, v102, v188
	v_cvt_pk_bf16_f32 v131, v102, v103
	v_add_f32_e32 v189, v103, v189
	s_waitcnt lgkmcnt(0)
	v_mfma_f32_32x32x16_bf16 v[48:63], v[190:193], v[128:131], v[48:63]
	s_mov_b32 m0, s22
	v_lshl_add_u64 v[176:177], v[156:157], 0, s[24:25]
	global_load_lds_dwordx4 v[176:177], off
	ds_read_b128 v[112:115], v136 offset:0
	ds_read_b128 v[116:119], v137 offset:0
	v_exp_f32_e32 v104, v104
	v_exp_f32_e32 v105, v105
	v_add_f32_e32 v188, v104, v188
	v_cvt_pk_bf16_f32 v132, v104, v105
	v_add_f32_e32 v189, v105, v189
	v_mfma_f32_32x32x16_bf16 v[32:47], v[194:197], v[128:131], v[32:47]
	s_add_i32 m0, s22, 0x8000
	v_lshl_add_u64 v[176:177], v[156:157], 0, s[8:9]
	global_load_lds_dwordx4 v[176:177], off
	ds_read_b128 v[120:123], v136 offset:4096
	ds_read_b128 v[124:127], v137 offset:4096
	v_exp_f32_e32 v106, v106
	v_exp_f32_e32 v107, v107
	v_add_f32_e32 v188, v106, v188
	v_cvt_pk_bf16_f32 v133, v106, v107
	v_add_f32_e32 v189, v107, v189
	v_mfma_f32_32x32x16_bf16 v[16:31], v[198:201], v[128:131], v[16:31]
	s_add_i32 m0, s69, 0x4000
	v_lshl_add_u64 v[178:179], s[80:81], 0, v[158:159]
	global_load_lds_dwordx4 v[178:179], off
	ds_read_b64_tr_b16 v[206:207], v170 offset:4096
	ds_read_b64_tr_b16 v[208:209], v170 offset:6144
	ds_read_b64_tr_b16 v[210:211], v171 offset:4096
	ds_read_b64_tr_b16 v[212:213], v171 offset:6144
	v_exp_f32_e32 v108, v108
	v_exp_f32_e32 v109, v109
	v_add_f32_e32 v188, v108, v188
	v_cvt_pk_bf16_f32 v134, v108, v109
	v_add_f32_e32 v189, v109, v189
	v_mfma_f32_32x32x16_bf16 v[0:15], v[202:205], v[128:131], v[0:15]
	s_add_i32 m0, s69, 0x4400
	v_lshl_add_u64 v[138:139], s[80:81], 0, v[160:161]
	global_load_lds_dwordx4 v[138:139], off
	ds_read_b64_tr_b16 v[214:215], v172 offset:4096
	ds_read_b64_tr_b16 v[216:217], v172 offset:6144
	ds_read_b64_tr_b16 v[218:219], v173 offset:4096
	ds_read_b64_tr_b16 v[220:221], v173 offset:6144
	v_exp_f32_e32 v110, v110
	v_exp_f32_e32 v111, v111
	v_add_f32_e32 v188, v110, v188
	v_cvt_pk_bf16_f32 v135, v110, v111
	v_add_f32_e32 v189, v111, v189
	s_waitcnt lgkmcnt(8)
	v_mfma_scale_f32_32x32x64_f8f6f4 v[96:111], v[112:119], v[144:151], v[64:79], v166, v166 op_sel_hi:[0,0,0]
	v_exp_f32_e32 v80, v80
	ds_read_b64_tr_b16 v[222:223], v170 offset:8192
	v_exp_f32_e32 v81, v81
	ds_read_b64_tr_b16 v[224:225], v170 offset:10240
	v_add_f32_e32 v188, v80, v188
	ds_read_b64_tr_b16 v[226:227], v171 offset:8192
	v_cvt_pk_bf16_f32 v128, v80, v81
	ds_read_b64_tr_b16 v[228:229], v171 offset:10240
	v_add_f32_e32 v189, v81, v189
	v_exp_f32_e32 v82, v82
	ds_read_b64_tr_b16 v[230:231], v172 offset:8192
	v_exp_f32_e32 v83, v83
	ds_read_b64_tr_b16 v[232:233], v172 offset:10240
	v_add_f32_e32 v188, v82, v188
	ds_read_b64_tr_b16 v[234:235], v173 offset:8192
	v_cvt_pk_bf16_f32 v129, v82, v83
	ds_read_b64_tr_b16 v[236:237], v173 offset:10240
	v_add_f32_e32 v189, v83, v189
	s_waitcnt lgkmcnt(8)
	v_mfma_f32_32x32x16_bf16 v[48:63], v[206:209], v[132:135], v[48:63]
	s_add_i32 m0, s69, 0xc000
	v_lshl_add_u64 v[178:179], s[4:5], 0, v[158:159]
	global_load_lds_dwordx4 v[178:179], off
	ds_read_b64_tr_b16 v[238:239], v170 offset:12288
	ds_read_b64_tr_b16 v[240:241], v170 offset:14336
	v_exp_f32_e32 v84, v84
	v_exp_f32_e32 v85, v85
	v_add_f32_e32 v188, v84, v188
	v_cvt_pk_bf16_f32 v130, v84, v85
	v_add_f32_e32 v189, v85, v189
	v_mfma_f32_32x32x16_bf16 v[32:47], v[210:213], v[132:135], v[32:47]
	s_add_i32 m0, s69, 0xc400
	v_lshl_add_u64 v[138:139], s[4:5], 0, v[160:161]
	global_load_lds_dwordx4 v[138:139], off
	ds_read_b64_tr_b16 v[242:243], v171 offset:12288
	ds_read_b64_tr_b16 v[244:245], v171 offset:14336
	v_exp_f32_e32 v86, v86
	v_exp_f32_e32 v87, v87
	v_add_f32_e32 v188, v86, v188
	v_cvt_pk_bf16_f32 v131, v86, v87
	v_add_f32_e32 v189, v87, v189
	v_mfma_f32_32x32x16_bf16 v[16:31], v[214:217], v[132:135], v[16:31]
	ds_read_b64_tr_b16 v[246:247], v172 offset:12288
	ds_read_b64_tr_b16 v[248:249], v172 offset:14336
	v_mfma_f32_32x32x16_bf16 v[0:15], v[218:221], v[132:135], v[0:15]
	ds_read_b64_tr_b16 v[250:251], v173 offset:12288
	ds_read_b64_tr_b16 v[252:253], v173 offset:14336
	s_waitcnt lgkmcnt(8)
; #define RAW_BARRIER() do { asm volatile("s_waitcnt lgkmcnt(0)" ::: "memory"); __builtin_amdgcn_s_barrier(); } while (0)
; #define SB() __builtin_amdgcn_sched_barrier(0)
; #define MV(g, st)                                                                                                     \
;   _Pragma("unroll") for (int eb = 0; eb < 4; ++eb)                                                                    \
;     oacc[eb] = MFMA32(__builtin_shufflevector(vlo[g][eb], vhi[g][eb], 0, 1, 2, 3, 4, 5, 6, 7), pf[st], oacc[eb]);
; #define EXP4(cx, i0) _Pragma("unroll") for (int i = (i0); i < (i0) + 4; ++i) { cx[i] = __builtin_amdgcn_exp2f(cx[i]); ps += cx[i]; }
; #define QK8(kf, cinit) __builtin_amdgcn_mfma_scale_f32_32x32x64_f8f6f4(kf, qf8, cinit, 0, 0, 0, 0x7F7F7F7F, 0, 0x7F7F7F7F)
; DI void attn_item(const Params& p, int L, int b, int h, int qb, float lam, char* lds) {
;     ...
;   auto step = [&](int t, f32x16& c0, f32x16& c1, f32x16& n0, f32x16& n1) {
;     if (t + 2 < nkt) asm volatile("s_waitcnt vmcnt(6)" ::: "memory");
;     else if (t + 1 < nkt) asm volatile("s_waitcnt vmcnt(3)" ::: "memory");
;     else asm volatile("s_waitcnt vmcnt(0)" ::: "memory");
;     RAW_BARRIER();
;     const int so = (t & 3) * A_STAGE;
;     int kad = so + kro, vad[4];
;     asm volatile("" : "+v"(kad));
; #pragma unroll
;     for (int i = 0; i < 4; ++i) { vad[i] = (int)lds_addr0 + so + vro[i]; asm volatile("" : "+v"(vad[i])); }
;     if (t + 3 < nkt) dma_tile(t + 3);
;     bf16x8 pf[4];
;     v8i_t kf0, kf1;
;     s16x4 vlo[2][4], vhi[2][4];
;     float ps = 0.f;
;     SB();
;     LDK8(kf0, kad) LDK8(kf1, kad + 32 * 128) RV(0, 0)
;     SB();
;     n0 = QK8(kf0, sv); EXP4(c0, 0) SB();
;     EXP4(c0, 4) PACK(pf[0], c0, 0) SB();
;     n1 = QK8(kf1, sv); EXP4(c0, 8) SB();
;     RV(1, 1) SB(); EXP4(c0, 12) PACK(pf[1], c0, 8) SB();
;     WAITV(8, 0) SB(); MVH(0, 0, 0) EXP4(c1, 0) SB(); MVH(0, 0, 2) EXP4(c1, 4) PACK(pf[2], c1, 0) SB();
;     RV(0, 2) SB(); WAITV(8, 1) SB(); MVH(1, 1, 0) EXP4(c1, 8) SB(); MVH(1, 1, 2) EXP4(c1, 12) PACK(pf[3], c1, 8) SB();
;     RV(1, 3) SB(); WAITV(8, 0) SB(); MV(0, 2) SB();
;     WAITV(0, 1) SB(); MV(1, 3) SB();
;     lsum += ps;
;   };
; #pragma nounroll
;   for (int t = 0; t < nkt; t += 2) {
;     step(t, sA0, sA1, sB0, sB1);
;     step(t + 1, sB0, sB1, sA0, sA1);
;   }
	v_mfma_f32_32x32x16_bf16 v[48:63], v[222:225], v[128:131], v[48:63]
	v_exp_f32_e32 v88, v88
	v_exp_f32_e32 v89, v89
	v_add_f32_e32 v188, v88, v188
	v_cvt_pk_bf16_f32 v132, v88, v89
	v_add_f32_e32 v189, v89, v189
	v_mfma_f32_32x32x16_bf16 v[32:47], v[226:229], v[128:131], v[32:47]
	v_exp_f32_e32 v90, v90
	v_exp_f32_e32 v91, v91
	v_add_f32_e32 v188, v90, v188
	v_cvt_pk_bf16_f32 v133, v90, v91
	v_add_f32_e32 v189, v91, v189
	v_mfma_f32_32x32x16_bf16 v[16:31], v[230:233], v[128:131], v[16:31]
	v_exp_f32_e32 v92, v92
	v_exp_f32_e32 v93, v93
	v_add_f32_e32 v188, v92, v188
	v_cvt_pk_bf16_f32 v134, v92, v93
	v_add_f32_e32 v189, v93, v189
	v_mfma_f32_32x32x16_bf16 v[0:15], v[234:237], v[128:131], v[0:15]
	v_exp_f32_e32 v94, v94
	v_exp_f32_e32 v95, v95
	v_add_f32_e32 v188, v94, v188
	v_cvt_pk_bf16_f32 v135, v94, v95
	v_add_f32_e32 v189, v95, v189
	v_mfma_scale_f32_32x32x64_f8f6f4 v[80:95], v[120:127], v[144:151], v[64:79], v166, v166 op_sel_hi:[0,0,0]
	s_waitcnt lgkmcnt(0)
	v_mfma_f32_32x32x16_bf16 v[48:63], v[238:241], v[132:135], v[48:63]
	ds_read_b64_tr_b16 v[190:191], v170 offset:32768
	ds_read_b64_tr_b16 v[192:193], v170 offset:34816
	ds_read_b64_tr_b16 v[194:195], v171 offset:32768
	ds_read_b64_tr_b16 v[196:197], v171 offset:34816
	v_mfma_f32_32x32x16_bf16 v[32:47], v[242:245], v[132:135], v[32:47]
	ds_read_b64_tr_b16 v[198:199], v172 offset:32768
	ds_read_b64_tr_b16 v[200:201], v172 offset:34816
	ds_read_b64_tr_b16 v[202:203], v173 offset:32768
	ds_read_b64_tr_b16 v[204:205], v173 offset:34816
	v_exp_f32_e32 v96, v96
	v_exp_f32_e32 v97, v97
	v_add_f32_e32 v188, v96, v188
	v_cvt_pk_bf16_f32 v128, v96, v97
	v_add_f32_e32 v189, v97, v189
	v_mfma_f32_32x32x16_bf16 v[16:31], v[246:249], v[132:135], v[16:31]
	v_exp_f32_e32 v98, v98
	v_exp_f32_e32 v99, v99
	v_add_f32_e32 v188, v98, v188
	v_cvt_pk_bf16_f32 v129, v98, v99
	v_add_f32_e32 v189, v99, v189
	v_mfma_f32_32x32x16_bf16 v[0:15], v[250:253], v[132:135], v[0:15]
	v_exp_f32_e32 v100, v100
	v_exp_f32_e32 v101, v101
	v_add_f32_e32 v188, v100, v188
	v_cvt_pk_bf16_f32 v130, v100, v101
	v_add_f32_e32 v189, v101, v189
	v_exp_f32_e32 v102, v102
	v_exp_f32_e32 v103, v103
	v_add_f32_e32 v188, v102, v188
	v_cvt_pk_bf16_f32 v131, v102, v103
	v_add_f32_e32 v189, v103, v189
	s_waitcnt lgkmcnt(0)
	v_mfma_f32_32x32x16_bf16 v[48:63], v[190:193], v[128:131], v[48:63]
	ds_read_b128 v[112:115], v136 offset:32768
	ds_read_b128 v[116:119], v137 offset:32768
	v_exp_f32_e32 v104, v104
	v_exp_f32_e32 v105, v105
	v_add_f32_e32 v188, v104, v188
	v_cvt_pk_bf16_f32 v132, v104, v105
	v_add_f32_e32 v189, v105, v189
	v_mfma_f32_32x32x16_bf16 v[32:47], v[194:197], v[128:131], v[32:47]
	ds_read_b128 v[120:123], v136 offset:36864
	ds_read_b128 v[124:127], v137 offset:36864
	v_exp_f32_e32 v106, v106
	v_exp_f32_e32 v107, v107
	v_add_f32_e32 v188, v106, v188
	v_cvt_pk_bf16_f32 v133, v106, v107
	v_add_f32_e32 v189, v107, v189
	v_mfma_f32_32x32x16_bf16 v[16:31], v[198:201], v[128:131], v[16:31]
	ds_read_b64_tr_b16 v[206:207], v170 offset:36864
	ds_read_b64_tr_b16 v[208:209], v170 offset:38912
	ds_read_b64_tr_b16 v[210:211], v171 offset:36864
	ds_read_b64_tr_b16 v[212:213], v171 offset:38912
	v_exp_f32_e32 v108, v108
	v_exp_f32_e32 v109, v109
	v_add_f32_e32 v188, v108, v188
	v_cvt_pk_bf16_f32 v134, v108, v109
	v_add_f32_e32 v189, v109, v189
	v_mfma_f32_32x32x16_bf16 v[0:15], v[202:205], v[128:131], v[0:15]
	ds_read_b64_tr_b16 v[214:215], v172 offset:36864
	ds_read_b64_tr_b16 v[216:217], v172 offset:38912
	ds_read_b64_tr_b16 v[218:219], v173 offset:36864
	ds_read_b64_tr_b16 v[220:221], v173 offset:38912
	v_exp_f32_e32 v110, v110
	v_exp_f32_e32 v111, v111
	v_add_f32_e32 v188, v110, v188
	v_cvt_pk_bf16_f32 v135, v110, v111
	v_add_f32_e32 v189, v111, v189
	s_waitcnt lgkmcnt(8)
	v_mfma_scale_f32_32x32x64_f8f6f4 v[96:111], v[112:119], v[144:151], v[64:79], v166, v166 op_sel_hi:[0,0,0]
	v_exp_f32_e32 v80, v80
	ds_read_b64_tr_b16 v[222:223], v170 offset:40960
	v_exp_f32_e32 v81, v81
	ds_read_b64_tr_b16 v[224:225], v170 offset:43008
	v_add_f32_e32 v188, v80, v188
	ds_read_b64_tr_b16 v[226:227], v171 offset:40960
	v_cvt_pk_bf16_f32 v128, v80, v81
	ds_read_b64_tr_b16 v[228:229], v171 offset:43008
	v_add_f32_e32 v189, v81, v189
	v_exp_f32_e32 v82, v82
	ds_read_b64_tr_b16 v[230:231], v172 offset:40960
	v_exp_f32_e32 v83, v83
	ds_read_b64_tr_b16 v[232:233], v172 offset:43008
	v_add_f32_e32 v188, v82, v188
	ds_read_b64_tr_b16 v[234:235], v173 offset:40960
	v_cvt_pk_bf16_f32 v129, v82, v83
	ds_read_b64_tr_b16 v[236:237], v173 offset:43008
	v_add_f32_e32 v189, v83, v189
	s_waitcnt lgkmcnt(8)
	v_mfma_f32_32x32x16_bf16 v[48:63], v[206:209], v[132:135], v[48:63]
	ds_read_b64_tr_b16 v[238:239], v170 offset:45056
	ds_read_b64_tr_b16 v[240:241], v170 offset:47104
	v_exp_f32_e32 v84, v84
	v_exp_f32_e32 v85, v85
	v_add_f32_e32 v188, v84, v188
	v_cvt_pk_bf16_f32 v130, v84, v85
	v_add_f32_e32 v189, v85, v189
	v_mfma_f32_32x32x16_bf16 v[32:47], v[210:213], v[132:135], v[32:47]
	ds_read_b64_tr_b16 v[242:243], v171 offset:45056
	ds_read_b64_tr_b16 v[244:245], v171 offset:47104
	v_exp_f32_e32 v86, v86
	v_exp_f32_e32 v87, v87
	v_add_f32_e32 v188, v86, v188
	v_cvt_pk_bf16_f32 v131, v86, v87
	v_add_f32_e32 v189, v87, v189
	v_mfma_f32_32x32x16_bf16 v[16:31], v[214:217], v[132:135], v[16:31]
	ds_read_b64_tr_b16 v[246:247], v172 offset:45056
	ds_read_b64_tr_b16 v[248:249], v172 offset:47104
	v_mfma_f32_32x32x16_bf16 v[0:15], v[218:221], v[132:135], v[0:15]
	ds_read_b64_tr_b16 v[250:251], v173 offset:45056
	ds_read_b64_tr_b16 v[252:253], v173 offset:47104
	s_waitcnt lgkmcnt(8)
	v_mfma_f32_32x32x16_bf16 v[48:63], v[222:225], v[128:131], v[48:63]
	v_exp_f32_e32 v88, v88
	v_exp_f32_e32 v89, v89
	v_add_f32_e32 v188, v88, v188
	v_cvt_pk_bf16_f32 v132, v88, v89
	v_add_f32_e32 v189, v89, v189
	v_mfma_f32_32x32x16_bf16 v[32:47], v[226:229], v[128:131], v[32:47]
	v_exp_f32_e32 v90, v90
	v_exp_f32_e32 v91, v91
	v_add_f32_e32 v188, v90, v188
	v_cvt_pk_bf16_f32 v133, v90, v91
	v_add_f32_e32 v189, v91, v189
	v_mfma_f32_32x32x16_bf16 v[16:31], v[230:233], v[128:131], v[16:31]
	v_exp_f32_e32 v92, v92
	v_exp_f32_e32 v93, v93
	v_add_f32_e32 v188, v92, v188
	v_cvt_pk_bf16_f32 v134, v92, v93
	v_add_f32_e32 v189, v93, v189
	v_mfma_f32_32x32x16_bf16 v[0:15], v[234:237], v[128:131], v[0:15]
	v_exp_f32_e32 v94, v94
	v_exp_f32_e32 v95, v95
	v_add_f32_e32 v188, v94, v188
	v_cvt_pk_bf16_f32 v135, v94, v95
	v_add_f32_e32 v189, v95, v189
	v_mfma_scale_f32_32x32x64_f8f6f4 v[80:95], v[120:127], v[144:151], v[64:79], v166, v166 op_sel_hi:[0,0,0]
	s_xor_b32 s84, s84, 0x10000
	s_xor_b32 s68, s68, 0x10000
	s_add_i32 s69, s68, s85
	s_add_i32 s22, s68, s59
	s_add_u32 s80, s80, 0x40000
	s_addc_u32 s81, s81, 0
	s_add_u32 s4, s4, 0x40000
	s_addc_u32 s5, s5, 0
	s_add_i32 s24, s24, 0x20000
	s_add_i32 s8, s24, 0x10000
	s_min_u32 s8, s8, s12
	s_add_i32 s23, s23, 2
	s_cmp_lt_u32 s23, s13
	s_cbranch_scc1 .Lat_top
; #define RAW_BARRIER() do { asm volatile("s_waitcnt lgkmcnt(0)" ::: "memory"); __builtin_amdgcn_s_barrier(); } while (0)
; #define SB() __builtin_amdgcn_sched_barrier(0)
; #define MV(g, st)                                                                                                     \
;   _Pragma("unroll") for (int eb = 0; eb < 4; ++eb)                                                                    \
;     oacc[eb] = MFMA32(__builtin_shufflevector(vlo[g][eb], vhi[g][eb], 0, 1, 2, 3, 4, 5, 6, 7), pf[st], oacc[eb]);
; #define EXP4(cx, i0) _Pragma("unroll") for (int i = (i0); i < (i0) + 4; ++i) { cx[i] = __builtin_amdgcn_exp2f(cx[i]); ps += cx[i]; }
; #define QK8(kf, cinit) __builtin_amdgcn_mfma_scale_f32_32x32x64_f8f6f4(kf, qf8, cinit, 0, 0, 0, 0x7F7F7F7F, 0, 0x7F7F7F7F)
; DI void attn_item(const Params& p, int L, int b, int h, int qb, float lam, char* lds) {
;     ...
;   auto step = [&](int t, f32x16& c0, f32x16& c1, f32x16& n0, f32x16& n1) {
;     if (t + 2 < nkt) asm volatile("s_waitcnt vmcnt(6)" ::: "memory");
;     else if (t + 1 < nkt) asm volatile("s_waitcnt vmcnt(3)" ::: "memory");
;     else asm volatile("s_waitcnt vmcnt(0)" ::: "memory");
;     RAW_BARRIER();
;     const int so = (t & 3) * A_STAGE;
;     int kad = so + kro, vad[4];
;     asm volatile("" : "+v"(kad));
; #pragma unroll
;     for (int i = 0; i < 4; ++i) { vad[i] = (int)lds_addr0 + so + vro[i]; asm volatile("" : "+v"(vad[i])); }
;     if (t + 3 < nkt) dma_tile(t + 3);
;     bf16x8 pf[4];
;     v8i_t kf0, kf1;
;     s16x4 vlo[2][4], vhi[2][4];
;     float ps = 0.f;
;     SB();
;     LDK8(kf0, kad) LDK8(kf1, kad + 32 * 128) RV(0, 0)
;     SB();
;     n0 = QK8(kf0, sv); EXP4(c0, 0) SB();
;     EXP4(c0, 4) PACK(pf[0], c0, 0) SB();
;     n1 = QK8(kf1, sv); EXP4(c0, 8) SB();
;     RV(1, 1) SB(); EXP4(c0, 12) PACK(pf[1], c0, 8) SB();
;     WAITV(8, 0) SB(); MVH(0, 0, 0) EXP4(c1, 0) SB(); MVH(0, 0, 2) EXP4(c1, 4) PACK(pf[2], c1, 0) SB();
;     RV(0, 2) SB(); WAITV(8, 1) SB(); MVH(1, 1, 0) EXP4(c1, 8) SB(); MVH(1, 1, 2) EXP4(c1, 12) PACK(pf[3], c1, 8) SB();
;     RV(1, 3) SB(); WAITV(8, 0) SB(); MV(0, 2) SB();
;     WAITV(0, 1) SB(); MV(1, 3) SB();
;     lsum += ps;
;   };
; #pragma nounroll
;   for (int t = 0; t < nkt; t += 2) {
;     step(t, sA0, sA1, sB0, sB1);
;     step(t + 1, sB0, sB1, sA0, sA1);
;   }
	s_waitcnt vmcnt(0)
	s_waitcnt lgkmcnt(0)
	s_barrier
	v_mfma_f32_32x32x16_bf16 v[48:63], v[238:241], v[132:135], v[48:63]
	v_add_u32_e32 v170, s84, v184
	v_add_u32_e32 v171, s84, v185
	ds_read_b64_tr_b16 v[190:191], v170 offset:0
	ds_read_b64_tr_b16 v[192:193], v170 offset:2048
	v_add_u32_e32 v172, s84, v186
	ds_read_b64_tr_b16 v[194:195], v171 offset:0
	ds_read_b64_tr_b16 v[196:197], v171 offset:2048
	v_mfma_f32_32x32x16_bf16 v[32:47], v[242:245], v[132:135], v[32:47]
	v_add_u32_e32 v173, s84, v187
	ds_read_b64_tr_b16 v[198:199], v172 offset:0
	ds_read_b64_tr_b16 v[200:201], v172 offset:2048
	ds_read_b64_tr_b16 v[202:203], v173 offset:0
	ds_read_b64_tr_b16 v[204:205], v173 offset:2048
	v_add_u32_e32 v136, s84, v183
	v_xor_b32_e32 v137, 16, v136
	v_exp_f32_e32 v96, v96
	v_exp_f32_e32 v97, v97
	v_add_f32_e32 v188, v96, v188
	v_cvt_pk_bf16_f32 v128, v96, v97
	v_add_f32_e32 v189, v97, v189
	v_mfma_f32_32x32x16_bf16 v[16:31], v[246:249], v[132:135], v[16:31]
	v_exp_f32_e32 v98, v98
	v_exp_f32_e32 v99, v99
	v_add_f32_e32 v188, v98, v188
	v_cvt_pk_bf16_f32 v129, v98, v99
	v_add_f32_e32 v189, v99, v189
	v_mfma_f32_32x32x16_bf16 v[0:15], v[250:253], v[132:135], v[0:15]
	v_exp_f32_e32 v100, v100
	v_exp_f32_e32 v101, v101
	v_add_f32_e32 v188, v100, v188
	v_cvt_pk_bf16_f32 v130, v100, v101
	v_add_f32_e32 v189, v101, v189
	v_exp_f32_e32 v102, v102
	v_exp_f32_e32 v103, v103
	v_add_f32_e32 v188, v102, v188
	v_cvt_pk_bf16_f32 v131, v102, v103
	v_add_f32_e32 v189, v103, v189
	s_waitcnt lgkmcnt(0)
	v_mfma_f32_32x32x16_bf16 v[48:63], v[190:193], v[128:131], v[48:63]
	ds_read_b128 v[112:115], v136 offset:0
	ds_read_b128 v[116:119], v137 offset:0
	v_exp_f32_e32 v104, v104
	v_exp_f32_e32 v105, v105
	v_add_f32_e32 v188, v104, v188
	v_cvt_pk_bf16_f32 v132, v104, v105
	v_add_f32_e32 v189, v105, v189
	v_mfma_f32_32x32x16_bf16 v[32:47], v[194:197], v[128:131], v[32:47]
	ds_read_b128 v[120:123], v136 offset:4096
	ds_read_b128 v[124:127], v137 offset:4096
	v_exp_f32_e32 v106, v106
	v_exp_f32_e32 v107, v107
	v_add_f32_e32 v188, v106, v188
	v_cvt_pk_bf16_f32 v133, v106, v107
	v_add_f32_e32 v189, v107, v189
	v_mfma_f32_32x32x16_bf16 v[16:31], v[198:201], v[128:131], v[16:31]
	ds_read_b64_tr_b16 v[206:207], v170 offset:4096
	ds_read_b64_tr_b16 v[208:209], v170 offset:6144
	ds_read_b64_tr_b16 v[210:211], v171 offset:4096
	ds_read_b64_tr_b16 v[212:213], v171 offset:6144
	v_exp_f32_e32 v108, v108
	v_exp_f32_e32 v109, v109
	v_add_f32_e32 v188, v108, v188
	v_cvt_pk_bf16_f32 v134, v108, v109
	v_add_f32_e32 v189, v109, v189
	v_mfma_f32_32x32x16_bf16 v[0:15], v[202:205], v[128:131], v[0:15]
	ds_read_b64_tr_b16 v[214:215], v172 offset:4096
	ds_read_b64_tr_b16 v[216:217], v172 offset:6144
	ds_read_b64_tr_b16 v[218:219], v173 offset:4096
	ds_read_b64_tr_b16 v[220:221], v173 offset:6144
	v_exp_f32_e32 v110, v110
	v_exp_f32_e32 v111, v111
	v_add_f32_e32 v188, v110, v188
	v_cvt_pk_bf16_f32 v135, v110, v111
	v_add_f32_e32 v189, v111, v189
	s_waitcnt lgkmcnt(8)
	v_mfma_scale_f32_32x32x64_f8f6f4 v[96:111], v[112:119], v[144:151], v[64:79], v166, v166 op_sel_hi:[0,0,0]
	v_exp_f32_e32 v80, v80
	ds_read_b64_tr_b16 v[222:223], v170 offset:8192
	v_exp_f32_e32 v81, v81
	ds_read_b64_tr_b16 v[224:225], v170 offset:10240
	v_add_f32_e32 v188, v80, v188
	ds_read_b64_tr_b16 v[226:227], v171 offset:8192
	v_cvt_pk_bf16_f32 v128, v80, v81
	ds_read_b64_tr_b16 v[228:229], v171 offset:10240
	v_add_f32_e32 v189, v81, v189
	v_exp_f32_e32 v82, v82
	ds_read_b64_tr_b16 v[230:231], v172 offset:8192
	v_exp_f32_e32 v83, v83
	ds_read_b64_tr_b16 v[232:233], v172 offset:10240
	v_add_f32_e32 v188, v82, v188
	ds_read_b64_tr_b16 v[234:235], v173 offset:8192
	v_cvt_pk_bf16_f32 v129, v82, v83
	ds_read_b64_tr_b16 v[236:237], v173 offset:10240
	v_add_f32_e32 v189, v83, v189
	s_waitcnt lgkmcnt(8)
	v_mfma_f32_32x32x16_bf16 v[48:63], v[206:209], v[132:135], v[48:63]
	ds_read_b64_tr_b16 v[238:239], v170 offset:12288
	ds_read_b64_tr_b16 v[240:241], v170 offset:14336
	v_exp_f32_e32 v84, v84
	v_exp_f32_e32 v85, v85
	v_add_f32_e32 v188, v84, v188
	v_cvt_pk_bf16_f32 v130, v84, v85
	v_add_f32_e32 v189, v85, v189
	v_mfma_f32_32x32x16_bf16 v[32:47], v[210:213], v[132:135], v[32:47]
	ds_read_b64_tr_b16 v[242:243], v171 offset:12288
	ds_read_b64_tr_b16 v[244:245], v171 offset:14336
	v_exp_f32_e32 v86, v86
	v_exp_f32_e32 v87, v87
	v_add_f32_e32 v188, v86, v188
	v_cvt_pk_bf16_f32 v131, v86, v87
	v_add_f32_e32 v189, v87, v189
	v_mfma_f32_32x32x16_bf16 v[16:31], v[214:217], v[132:135], v[16:31]
	ds_read_b64_tr_b16 v[246:247], v172 offset:12288
	ds_read_b64_tr_b16 v[248:249], v172 offset:14336
	v_mfma_f32_32x32x16_bf16 v[0:15], v[218:221], v[132:135], v[0:15]
	ds_read_b64_tr_b16 v[250:251], v173 offset:12288
	ds_read_b64_tr_b16 v[252:253], v173 offset:14336
	s_waitcnt lgkmcnt(8)
	v_mfma_f32_32x32x16_bf16 v[48:63], v[222:225], v[128:131], v[48:63]
	v_exp_f32_e32 v88, v88
	v_exp_f32_e32 v89, v89
	v_add_f32_e32 v188, v88, v188
	v_cvt_pk_bf16_f32 v132, v88, v89
	v_add_f32_e32 v189, v89, v189
	v_mfma_f32_32x32x16_bf16 v[32:47], v[226:229], v[128:131], v[32:47]
	v_exp_f32_e32 v90, v90
	v_exp_f32_e32 v91, v91
	v_add_f32_e32 v188, v90, v188
	v_cvt_pk_bf16_f32 v133, v90, v91
	v_add_f32_e32 v189, v91, v189
	v_mfma_f32_32x32x16_bf16 v[16:31], v[230:233], v[128:131], v[16:31]
	v_exp_f32_e32 v92, v92
	v_exp_f32_e32 v93, v93
	v_add_f32_e32 v188, v92, v188
	v_cvt_pk_bf16_f32 v134, v92, v93
	v_add_f32_e32 v189, v93, v189
	v_mfma_f32_32x32x16_bf16 v[0:15], v[234:237], v[128:131], v[0:15]
	v_exp_f32_e32 v94, v94
	v_exp_f32_e32 v95, v95
	v_add_f32_e32 v188, v94, v188
	v_cvt_pk_bf16_f32 v135, v94, v95
	v_add_f32_e32 v189, v95, v189
	v_mfma_scale_f32_32x32x64_f8f6f4 v[80:95], v[120:127], v[144:151], v[64:79], v166, v166 op_sel_hi:[0,0,0]
	s_waitcnt lgkmcnt(0)
; #define SB() __builtin_amdgcn_sched_barrier(0)
; #define MV(g, st)                                                                                                     \
;   _Pragma("unroll") for (int eb = 0; eb < 4; ++eb)                                                                    \
;     oacc[eb] = MFMA32(__builtin_shufflevector(vlo[g][eb], vhi[g][eb], 0, 1, 2, 3, 4, 5, 6, 7), pf[st], oacc[eb]);
; #define EXP4(cx, i0) _Pragma("unroll") for (int i = (i0); i < (i0) + 4; ++i) { cx[i] = __builtin_amdgcn_exp2f(cx[i]); ps += cx[i]; }
; #define MVH(g, st, e0)                                                                                                \
;   oacc[e0] = MFMA32(__builtin_shufflevector(vlo[g][e0], vhi[g][e0], 0, 1, 2, 3, 4, 5, 6, 7), pf[st], oacc[e0]);       \
;   oacc[(e0) + 1] = MFMA32(__builtin_shufflevector(vlo[g][(e0) + 1], vhi[g][(e0) + 1], 0, 1, 2, 3, 4, 5, 6, 7), pf[st], oacc[(e0) + 1]);
; #define QK8(kf, cinit) __builtin_amdgcn_mfma_scale_f32_32x32x64_f8f6f4(kf, qf8, cinit, 0, 0, 0, 0x7F7F7F7F, 0, 0x7F7F7F7F)
; DI void attn_item(const Params& p, int L, int b, int h, int qb, float lam, char* lds) {
;     ...
;     LDK8(kf0, kad) LDK8(kf1, kad + 32 * 128) RV(0, 0)
;     SB();
;     n0 = QK8(kf0, sv); EXP4(c0, 0) SB();
;     EXP4(c0, 4) PACK(pf[0], c0, 0) SB();
;     n1 = QK8(kf1, sv); EXP4(c0, 8) SB();
;     RV(1, 1) SB(); EXP4(c0, 12) PACK(pf[1], c0, 8) SB();
;     WAITV(8, 0) SB(); MVH(0, 0, 0) EXP4(c1, 0) SB(); MVH(0, 0, 2) EXP4(c1, 4) PACK(pf[2], c1, 0) SB();
;     RV(0, 2) SB(); WAITV(8, 1) SB(); MVH(1, 1, 0) EXP4(c1, 8) SB(); MVH(1, 1, 2) EXP4(c1, 12) PACK(pf[3], c1, 8) SB();
;     RV(1, 3) SB(); WAITV(8, 0) SB(); MV(0, 2) SB();
;     WAITV(0, 1) SB(); MV(1, 3) SB();
;     lsum += ps;
;   };
; #pragma nounroll
;   for (int t = 0; t < nkt; t += 2) {
;     step(t, sA0, sA1, sB0, sB1);
;     step(t + 1, sB0, sB1, sA0, sA1);
;   }
;     ...
;   __syncthreads();
;   const float ltot = xhalf_sum(lsum);
	v_mfma_f32_32x32x16_bf16 v[48:63], v[238:241], v[132:135], v[48:63]
	ds_read_b64_tr_b16 v[190:191], v170 offset:32768
	ds_read_b64_tr_b16 v[192:193], v170 offset:34816
	ds_read_b64_tr_b16 v[194:195], v171 offset:32768
	ds_read_b64_tr_b16 v[196:197], v171 offset:34816
	v_mfma_f32_32x32x16_bf16 v[32:47], v[242:245], v[132:135], v[32:47]
	ds_read_b64_tr_b16 v[198:199], v172 offset:32768
	ds_read_b64_tr_b16 v[200:201], v172 offset:34816
	ds_read_b64_tr_b16 v[202:203], v173 offset:32768
	ds_read_b64_tr_b16 v[204:205], v173 offset:34816
	v_exp_f32_e32 v96, v96
	v_exp_f32_e32 v97, v97
	v_add_f32_e32 v188, v96, v188
	v_cvt_pk_bf16_f32 v128, v96, v97
	v_add_f32_e32 v189, v97, v189
	v_mfma_f32_32x32x16_bf16 v[16:31], v[246:249], v[132:135], v[16:31]
	v_exp_f32_e32 v98, v98
	v_exp_f32_e32 v99, v99
	v_add_f32_e32 v188, v98, v188
	v_cvt_pk_bf16_f32 v129, v98, v99
	v_add_f32_e32 v189, v99, v189
	v_mfma_f32_32x32x16_bf16 v[0:15], v[250:253], v[132:135], v[0:15]
	v_exp_f32_e32 v100, v100
	v_exp_f32_e32 v101, v101
	v_add_f32_e32 v188, v100, v188
	v_cvt_pk_bf16_f32 v130, v100, v101
	v_add_f32_e32 v189, v101, v189
	v_exp_f32_e32 v102, v102
	v_exp_f32_e32 v103, v103
	v_add_f32_e32 v188, v102, v188
	v_cvt_pk_bf16_f32 v131, v102, v103
	v_add_f32_e32 v189, v103, v189
	s_waitcnt lgkmcnt(0)
	v_mfma_f32_32x32x16_bf16 v[48:63], v[190:193], v[128:131], v[48:63]
	ds_read_b128 v[112:115], v136 offset:32768
	ds_read_b128 v[116:119], v137 offset:32768
	v_exp_f32_e32 v104, v104
	v_exp_f32_e32 v105, v105
	v_add_f32_e32 v188, v104, v188
	v_cvt_pk_bf16_f32 v132, v104, v105
	v_add_f32_e32 v189, v105, v189
	v_mfma_f32_32x32x16_bf16 v[32:47], v[194:197], v[128:131], v[32:47]
	ds_read_b128 v[120:123], v136 offset:36864
	ds_read_b128 v[124:127], v137 offset:36864
	v_exp_f32_e32 v106, v106
	v_exp_f32_e32 v107, v107
	v_add_f32_e32 v188, v106, v188
	v_cvt_pk_bf16_f32 v133, v106, v107
	v_add_f32_e32 v189, v107, v189
	v_mfma_f32_32x32x16_bf16 v[16:31], v[198:201], v[128:131], v[16:31]
	ds_read_b64_tr_b16 v[206:207], v170 offset:36864
	ds_read_b64_tr_b16 v[208:209], v170 offset:38912
	ds_read_b64_tr_b16 v[210:211], v171 offset:36864
	ds_read_b64_tr_b16 v[212:213], v171 offset:38912
	v_exp_f32_e32 v108, v108
	v_exp_f32_e32 v109, v109
	v_add_f32_e32 v188, v108, v188
	v_cvt_pk_bf16_f32 v134, v108, v109
	v_add_f32_e32 v189, v109, v189
	v_mfma_f32_32x32x16_bf16 v[0:15], v[202:205], v[128:131], v[0:15]
	ds_read_b64_tr_b16 v[214:215], v172 offset:36864
	ds_read_b64_tr_b16 v[216:217], v172 offset:38912
	ds_read_b64_tr_b16 v[218:219], v173 offset:36864
	ds_read_b64_tr_b16 v[220:221], v173 offset:38912
	v_exp_f32_e32 v110, v110
	v_exp_f32_e32 v111, v111
	v_add_f32_e32 v188, v110, v188
	v_cvt_pk_bf16_f32 v135, v110, v111
	v_add_f32_e32 v189, v111, v189
	s_waitcnt lgkmcnt(8)
	v_mfma_scale_f32_32x32x64_f8f6f4 v[96:111], v[112:119], v[144:151], v[64:79], v166, v166 op_sel_hi:[0,0,0]
	v_exp_f32_e32 v80, v80
	ds_read_b64_tr_b16 v[222:223], v170 offset:40960
	v_exp_f32_e32 v81, v81
	ds_read_b64_tr_b16 v[224:225], v170 offset:43008
	v_add_f32_e32 v188, v80, v188
	ds_read_b64_tr_b16 v[226:227], v171 offset:40960
	v_cvt_pk_bf16_f32 v128, v80, v81
	ds_read_b64_tr_b16 v[228:229], v171 offset:43008
	v_add_f32_e32 v189, v81, v189
	v_exp_f32_e32 v82, v82
	ds_read_b64_tr_b16 v[230:231], v172 offset:40960
	v_exp_f32_e32 v83, v83
	ds_read_b64_tr_b16 v[232:233], v172 offset:43008
	v_add_f32_e32 v188, v82, v188
	ds_read_b64_tr_b16 v[234:235], v173 offset:40960
	v_cvt_pk_bf16_f32 v129, v82, v83
	ds_read_b64_tr_b16 v[236:237], v173 offset:43008
	v_add_f32_e32 v189, v83, v189
	s_waitcnt lgkmcnt(8)
	v_mfma_f32_32x32x16_bf16 v[48:63], v[206:209], v[132:135], v[48:63]
	ds_read_b64_tr_b16 v[238:239], v170 offset:45056
	ds_read_b64_tr_b16 v[240:241], v170 offset:47104
	v_exp_f32_e32 v84, v84
	v_exp_f32_e32 v85, v85
	v_add_f32_e32 v188, v84, v188
	v_cvt_pk_bf16_f32 v130, v84, v85
	v_add_f32_e32 v189, v85, v189
	v_mfma_f32_32x32x16_bf16 v[32:47], v[210:213], v[132:135], v[32:47]
	ds_read_b64_tr_b16 v[242:243], v171 offset:45056
	ds_read_b64_tr_b16 v[244:245], v171 offset:47104
	v_exp_f32_e32 v86, v86
	v_exp_f32_e32 v87, v87
	v_add_f32_e32 v188, v86, v188
	v_cvt_pk_bf16_f32 v131, v86, v87
	v_add_f32_e32 v189, v87, v189
	v_mfma_f32_32x32x16_bf16 v[16:31], v[214:217], v[132:135], v[16:31]
	ds_read_b64_tr_b16 v[246:247], v172 offset:45056
	ds_read_b64_tr_b16 v[248:249], v172 offset:47104
	v_mfma_f32_32x32x16_bf16 v[0:15], v[218:221], v[132:135], v[0:15]
	ds_read_b64_tr_b16 v[250:251], v173 offset:45056
	ds_read_b64_tr_b16 v[252:253], v173 offset:47104
	s_waitcnt lgkmcnt(8)
	v_mfma_f32_32x32x16_bf16 v[48:63], v[222:225], v[128:131], v[48:63]
	v_exp_f32_e32 v88, v88
	v_exp_f32_e32 v89, v89
	v_add_f32_e32 v188, v88, v188
	v_cvt_pk_bf16_f32 v132, v88, v89
	v_add_f32_e32 v189, v89, v189
	v_mfma_f32_32x32x16_bf16 v[32:47], v[226:229], v[128:131], v[32:47]
	v_exp_f32_e32 v90, v90
	v_exp_f32_e32 v91, v91
	v_add_f32_e32 v188, v90, v188
	v_cvt_pk_bf16_f32 v133, v90, v91
	v_add_f32_e32 v189, v91, v189
	v_mfma_f32_32x32x16_bf16 v[16:31], v[230:233], v[128:131], v[16:31]
	v_exp_f32_e32 v92, v92
	v_exp_f32_e32 v93, v93
	v_add_f32_e32 v188, v92, v188
	v_cvt_pk_bf16_f32 v134, v92, v93
	v_add_f32_e32 v189, v93, v189
	v_mfma_f32_32x32x16_bf16 v[0:15], v[234:237], v[128:131], v[0:15]
	v_exp_f32_e32 v94, v94
	v_exp_f32_e32 v95, v95
	v_add_f32_e32 v188, v94, v188
	v_cvt_pk_bf16_f32 v135, v94, v95
	v_add_f32_e32 v189, v95, v189
	v_mfma_scale_f32_32x32x64_f8f6f4 v[80:95], v[120:127], v[144:151], v[64:79], v166, v166 op_sel_hi:[0,0,0]
	s_waitcnt lgkmcnt(0)
	v_mfma_f32_32x32x16_bf16 v[48:63], v[238:241], v[132:135], v[48:63]
	v_mfma_f32_32x32x16_bf16 v[32:47], v[242:245], v[132:135], v[32:47]
	v_mfma_f32_32x32x16_bf16 v[16:31], v[246:249], v[132:135], v[16:31]
	v_mfma_f32_32x32x16_bf16 v[0:15], v[250:253], v[132:135], v[0:15]
	s_setprio 0
	v_add_f32_e32 v188, v188, v189

; __global__ void __launch_bounds__(NT) fwd_megakernel(Params p) {
;     ...
;     phase_attn(p, hf, lds);
;     grid.sync();
.LBB0_229:
	s_barrier
	s_mov_b64 s[4:5], exec
	v_readlane_b32 s0, v254, 34
	v_readlane_b32 s1, v254, 35
	v_readlane_b32 s84, v254, 14
	s_mov_b32 s58, s14
	v_readlane_b32 s14, v254, 36
	s_and_b64 s[0:1], s[4:5], s[0:1]
	v_readlane_b32 s85, v254, 15
	s_movk_i32 s96, 0x7fff
	v_readlane_b32 s15, v254, 37
	s_mov_b64 exec, s[0:1]
	s_cbranch_execz .LBB0_239
	v_readlane_b32 s0, v254, 0
	v_readlane_b32 s1, v254, 1
	buffer_wbl2 sc1
	s_waitcnt vmcnt(0)
	v_readlane_b32 s0, v254, 2
	v_readlane_b32 s1, v254, 3
	v_readlane_b32 s24, v255, 50
	v_readlane_b32 s25, v254, 4
	v_readlane_b32 s80, v254, 5
	s_nop 3
	s_load_dwordx2 s[8:9], s[0:1], 0x128
	s_add_i32 s24, s24, 1
	v_writelane_b32 v255, s24, 50
	s_and_b32 s25, s25, 7
	s_sub_i32 s81, s80, s25
	s_add_i32 s81, s81, 7
	s_lshr_b32 s81, s81, 3
	s_mul_i32 s81, s81, s24
	s_min_u32 s80, s80, 8
	s_mul_i32 s80, s80, s24
	s_lshl_b32 s25, s25, 5
	v_mov_b32_e32 v0, s25
	v_mov_b32_e32 v1, 1
	s_waitcnt lgkmcnt(0)
	s_add_u32 s8, s8, 0x43a4000
	s_addc_u32 s9, s9, 0
	global_atomic_add v2, v0, v1, s[8:9] offset:512 sc0
	s_waitcnt vmcnt(0)
	v_readfirstlane_b32 s0, v2
	s_nop 3
	s_add_i32 s0, s0, 1
	s_cmp_eq_u32 s0, s81
	s_cbranch_scc0 .Lgs4_follower
	global_atomic_add v2, v153, v1, s[8:9] offset:64 sc0
	s_waitcnt vmcnt(0)
	v_readfirstlane_b32 s0, v2
	s_nop 3
	s_add_i32 s0, s0, 1
	s_cmp_eq_u32 s0, s80
	s_cbranch_scc0 .Lgs4_lwait
	global_atomic_add v153, v1, s[8:9] offset:128
	s_branch .Lgs4_lrel

; __global__ void __launch_bounds__(NT) fwd_megakernel(Params p) {
;     ...
;     phase_ssm_out(p, lds);
;     grid.sync();
.LBB0_249:
	s_barrier
	s_mov_b64 s[4:5], exec
	v_readlane_b32 s0, v254, 34
	v_readlane_b32 s1, v254, 35
	s_and_b64 s[0:1], s[4:5], s[0:1]
	s_mov_b64 exec, s[0:1]
	s_cbranch_execz .LBB0_259
	v_readlane_b32 s0, v254, 0
	v_readlane_b32 s1, v254, 1
	buffer_wbl2 sc1
	s_waitcnt vmcnt(0)
	v_readlane_b32 s0, v254, 2
	v_readlane_b32 s1, v254, 3
	v_readlane_b32 s24, v255, 50
	v_readlane_b32 s25, v254, 4
	v_readlane_b32 s80, v254, 5
	s_nop 3
	s_load_dwordx2 s[8:9], s[0:1], 0x128
	s_add_i32 s24, s24, 1
	v_writelane_b32 v255, s24, 50
	s_and_b32 s25, s25, 7
	s_sub_i32 s81, s80, s25
	s_add_i32 s81, s81, 7
	s_lshr_b32 s81, s81, 3
	s_mul_i32 s81, s81, s24
	s_min_u32 s80, s80, 8
	s_mul_i32 s80, s80, s24
	s_lshl_b32 s25, s25, 5
	v_mov_b32_e32 v0, s25
	v_mov_b32_e32 v1, 1
	s_waitcnt lgkmcnt(0)
	s_add_u32 s8, s8, 0x43a4000
	s_addc_u32 s9, s9, 0
	global_atomic_add v2, v0, v1, s[8:9] offset:512 sc0
	s_waitcnt vmcnt(0)
	v_readfirstlane_b32 s0, v2
	s_nop 3
	s_add_i32 s0, s0, 1
	s_cmp_eq_u32 s0, s81
	s_cbranch_scc0 .Lgs5_follower
	global_atomic_add v2, v153, v1, s[8:9] offset:64 sc0
	s_waitcnt vmcnt(0)
	v_readfirstlane_b32 s0, v2
	s_nop 3
	s_add_i32 s0, s0, 1
	s_cmp_eq_u32 s0, s80
	s_cbranch_scc0 .Lgs5_lwait
	global_atomic_add v153, v1, s[8:9] offset:128
	s_branch .Lgs5_lrel

; __global__ void __launch_bounds__(NT) fwd_megakernel(Params p) {
;     ...
;     phase_gemm_plain<false>((const bf16_t*)(p.ws + OFF_K), 1024, (const bf16_t*)(p.ws + OFF_WOUT), 1024, (bf16_t*)(p.ws + OFF_V), lds);
;     grid.sync();
.LBB0_313:
	s_waitcnt vmcnt(0)
	s_barrier
	s_mov_b64 s[4:5], exec
	v_readlane_b32 s0, v254, 34
	v_readlane_b32 s1, v254, 35
	s_and_b64 s[0:1], s[4:5], s[0:1]
	s_mov_b32 s21, 0x800000
	s_mov_b64 exec, s[0:1]
	s_cbranch_execz .LBB0_323
	v_readlane_b32 s0, v254, 0
	v_readlane_b32 s1, v254, 1
	buffer_wbl2 sc1
	s_waitcnt vmcnt(0)
	v_readlane_b32 s0, v254, 2
	v_readlane_b32 s1, v254, 3
	v_readlane_b32 s24, v255, 50
	v_readlane_b32 s25, v254, 4
	v_readlane_b32 s80, v254, 5
	s_nop 3
	s_load_dwordx2 s[8:9], s[0:1], 0x128
	s_add_i32 s24, s24, 1
	v_writelane_b32 v255, s24, 50
	s_and_b32 s25, s25, 7
	s_sub_i32 s81, s80, s25
	s_add_i32 s81, s81, 7
	s_lshr_b32 s81, s81, 3
	s_mul_i32 s81, s81, s24
	s_min_u32 s80, s80, 8
	s_mul_i32 s80, s80, s24
	s_lshl_b32 s25, s25, 5
	v_mov_b32_e32 v0, s25
	v_mov_b32_e32 v1, 1
	s_waitcnt lgkmcnt(0)
	s_add_u32 s8, s8, 0x43a4000
	s_addc_u32 s9, s9, 0
	global_atomic_add v2, v0, v1, s[8:9] offset:512 sc0
	s_waitcnt vmcnt(0)
	v_readfirstlane_b32 s0, v2
	s_nop 3
	s_add_i32 s0, s0, 1
	s_cmp_eq_u32 s0, s81
	s_cbranch_scc0 .Lgs8_follower
	global_atomic_add v2, v153, v1, s[8:9] offset:64 sc0
	s_waitcnt vmcnt(0)
	v_readfirstlane_b32 s0, v2
	s_nop 3
	s_add_i32 s0, s0, 1
	s_cmp_eq_u32 s0, s80
	s_cbranch_scc0 .Lgs8_lwait
	global_atomic_add v153, v1, s[8:9] offset:128
	s_branch .Lgs8_lrel

; __global__ void __launch_bounds__(NT) fwd_megakernel(Params p) {
;     ...
;     phase_x1(p, hf);
;     grid.sync();
.LBB0_326:
	s_or_b64 exec, exec, s[8:9]
	s_barrier
	s_mov_b64 s[8:9], exec
	v_readlane_b32 s0, v254, 34
	v_readlane_b32 s1, v254, 35
	s_and_b64 s[0:1], s[8:9], s[0:1]
	s_mov_b64 exec, s[0:1]
	s_cbranch_execz .LBB0_336
	v_readlane_b32 s0, v254, 0
	v_readlane_b32 s1, v254, 1
	buffer_wbl2 sc1
	s_waitcnt vmcnt(0)
	v_readlane_b32 s0, v254, 2
	v_readlane_b32 s1, v254, 3
	v_readlane_b32 s80, v255, 50
	v_readlane_b32 s81, v254, 4
	v_readlane_b32 s82, v254, 5
	s_nop 3
	s_load_dwordx2 s[24:25], s[0:1], 0x128
	s_add_i32 s80, s80, 1
	v_writelane_b32 v255, s80, 50
	s_and_b32 s81, s81, 7
	s_sub_i32 s83, s82, s81
	s_add_i32 s83, s83, 7
	s_lshr_b32 s83, s83, 3
	s_mul_i32 s83, s83, s80
	s_min_u32 s82, s82, 8
	s_mul_i32 s82, s82, s80
	s_lshl_b32 s81, s81, 5
	v_mov_b32_e32 v0, s81
	v_mov_b32_e32 v1, 1
	s_waitcnt lgkmcnt(0)
	s_add_u32 s24, s24, 0x43a4000
	s_addc_u32 s25, s25, 0
	global_atomic_add v2, v0, v1, s[24:25] offset:512 sc0
	s_waitcnt vmcnt(0)
	v_readfirstlane_b32 s0, v2
	s_nop 3
	s_add_i32 s0, s0, 1
	s_cmp_eq_u32 s0, s83
	s_cbranch_scc0 .Lgs9_follower
	global_atomic_add v2, v153, v1, s[24:25] offset:64 sc0
	s_waitcnt vmcnt(0)
	v_readfirstlane_b32 s0, v2
	s_nop 3
	s_add_i32 s0, s0, 1
	s_cmp_eq_u32 s0, s82
	s_cbranch_scc0 .Lgs9_lwait
	global_atomic_add v153, v1, s[24:25] offset:128
	s_branch .Lgs9_lrel

; __global__ void __launch_bounds__(NT) fwd_megakernel(Params p) {
;     ...
;     phase_x1(p, hf);
;     grid.sync();
.Lgs9_lspin:
	s_sleep 2
	global_atomic_add v2, v153, v153, s[24:25] offset:128 sc0
	s_add_i32 s1, s1, 1
	s_waitcnt vmcnt(0)
	v_readfirstlane_b32 s0, v2
	s_nop 3
	s_cmp_ge_u32 s0, s80
	s_cbranch_scc1 .Lgs9_lrel
	s_cmp_lt_u32 s1, 0x4000
	s_cbranch_scc1 .Lgs9_lspin
.Lgs9_lrel:
	global_atomic_add v0, v1, s[24:25] offset:768
	s_branch .Lgs9_done

; __global__ void __launch_bounds__(NT) fwd_megakernel(Params p) {
;     ...
;     phase_x1(p, hf);
;     grid.sync();
.Lgs9_fspin:
	s_sleep 8
	global_atomic_add v2, v0, v153, s[24:25] offset:768 sc0
	s_add_i32 s1, s1, 1
	s_waitcnt vmcnt(0)
	v_readfirstlane_b32 s0, v2
	s_nop 3
	s_cmp_ge_u32 s0, s80
	s_cbranch_scc1 .Lgs9_done
	s_cmp_lt_u32 s1, 0x4000
	s_cbranch_scc1 .Lgs9_fspin

; __global__ void __launch_bounds__(NT) fwd_megakernel(Params p) {
;     ...
;     phase_gemm_plain<true>((const bf16_t*)(p.ws + OFF_H1), 1024, (const bf16_t*)(p.ws + OFF_WFF1), 4096, (bf16_t*)(p.ws + OFF_Q), lds);
;     grid.sync();
.LBB0_337:
	s_waitcnt vmcnt(0)
	s_barrier
	s_mov_b64 s[8:9], exec
	v_readlane_b32 s0, v254, 34
	v_readlane_b32 s1, v254, 35
	s_and_b64 s[0:1], s[8:9], s[0:1]
	s_mov_b64 exec, s[0:1]
	s_cbranch_execz .LBB0_347
	v_readlane_b32 s0, v254, 0
	v_readlane_b32 s1, v254, 1
	buffer_wbl2 sc1
	s_waitcnt vmcnt(0)
	v_readlane_b32 s0, v254, 2
	v_readlane_b32 s1, v254, 3
	v_readlane_b32 s80, v255, 50
	v_readlane_b32 s81, v254, 4
	v_readlane_b32 s82, v254, 5
	s_nop 3
	s_load_dwordx2 s[24:25], s[0:1], 0x128
	s_add_i32 s80, s80, 1
	v_writelane_b32 v255, s80, 50
	s_and_b32 s81, s81, 7
	s_sub_i32 s83, s82, s81
	s_add_i32 s83, s83, 7
	s_lshr_b32 s83, s83, 3
	s_mul_i32 s83, s83, s80
	s_min_u32 s82, s82, 8
	s_mul_i32 s82, s82, s80
	s_lshl_b32 s81, s81, 5
	v_mov_b32_e32 v0, s81
	v_mov_b32_e32 v1, 1
	s_waitcnt lgkmcnt(0)
	s_add_u32 s24, s24, 0x43a4000
	s_addc_u32 s25, s25, 0
	global_atomic_add v2, v0, v1, s[24:25] offset:512 sc0
	s_waitcnt vmcnt(0)
	v_readfirstlane_b32 s0, v2
	s_nop 3
	s_add_i32 s0, s0, 1
	s_cmp_eq_u32 s0, s83
	s_cbranch_scc0 .Lgs10_follower
	global_atomic_add v2, v153, v1, s[24:25] offset:64 sc0
	s_waitcnt vmcnt(0)
	v_readfirstlane_b32 s0, v2
	s_nop 3
	s_add_i32 s0, s0, 1
	s_cmp_eq_u32 s0, s82
	s_cbranch_scc0 .Lgs10_lwait
	global_atomic_add v153, v1, s[24:25] offset:128
	s_branch .Lgs10_lrel

; __global__ void __launch_bounds__(NT) fwd_megakernel(Params p) {
;     ...
;     phase_final(p, hf);
;     grid.sync();
.LBB0_385:
	s_sleep 32
	global_load_dword v1, v153, s[8:9] offset:32 sc1
	s_waitcnt vmcnt(0)
	v_and_b32_e32 v1, 0xffff0000, v1
	v_cmp_ne_u32_e32 vcc, v1, v0
	s_or_b64 s[24:25], vcc, s[24:25]
	s_andn2_b64 exec, exec, s[24:25]
	s_cbranch_execnz .LBB0_385
	s_getpc_b64 s[98:99]
